# adds: GDN staging as packed 32-bit LDS writes, earlier next-chunk prefetch for latent GDN items, HGRN wave halves run prep/recurrence in opposite order (complementary SIMD partners)
# speedup vs baseline: 1.0457x; 1.0070x over previous
.LBB0_359:
	s_andn2_b64 vcc, exec, s[10:11]
	s_cbranch_vccnz .LBB0_361
	s_waitcnt lgkmcnt(1)
	v_mul_f32_e32 v124, 0x3fb8aa3b, v147
	v_exp_f32_e32 v124, v124
	s_waitcnt lgkmcnt(0)
	v_mul_f32_e32 v125, 0x3fb8aa3b, v144
	v_sub_f32_e32 v126, s63, v147
	v_exp_f32_e32 v125, v125
	v_mul_f32_e32 v126, 0x3fb8aa3b, v126
	v_exp_f32_e32 v126, v126
	v_sub_f32_e32 v127, s63, v144
	v_mul_f32_e32 v124, v141, v124
	v_mul_f32_e32 v127, 0x3fb8aa3b, v127
	v_exp_f32_e32 v127, v127
	v_mul_f32_e32 v128, v124, v120
	v_mad_u32_u24 v129, v206, s73, v143
	v_mul_f32_e32 v125, v0, v125
	v_cvt_pk_bf16_f32 v128, v128, s0
	v_lshl_add_u32 v129, v129, 1, 0
	ds_write_b128 v145, v[84:87]
	ds_write_b128 v146, v[96:99]
	ds_write_b128 v145, v[88:91] offset:17408
	ds_write_b128 v146, v[100:103] offset:17408
	v_mad_u32_u24 v130, v206, s73, v142
	v_lshl_add_u32 v130, v130, 1, 0
	s_cmp_lg_u64 s[4:5], 0
	s_cselect_b32 s10, 0, 16
	v_min_u32_e32 v131, v129, v130
	v_mul_f32_e32 v132, v124, v120
	v_mul_f32_e32 v133, v125, v122
	v_mul_f32_e32 v134, v126, v120
	v_mul_f32_e32 v135, v127, v122
	v_cvt_pk_bf16_f32 v132, v132, v133
	v_cvt_pk_bf16_f32 v134, v134, v135
	v_alignbit_b32 v132, v132, v132, s10
	v_alignbit_b32 v134, v134, v134, s10
	ds_write_b32 v131, v132 offset:34816
	ds_write_b32 v131, v134 offset:53248
	v_mul_f32_e32 v132, v124, v121
	v_mul_f32_e32 v133, v125, v123
	v_mul_f32_e32 v134, v126, v121
	v_mul_f32_e32 v135, v127, v123
	v_cvt_pk_bf16_f32 v132, v132, v133
	v_cvt_pk_bf16_f32 v134, v134, v135
	v_alignbit_b32 v132, v132, v132, s10
	v_alignbit_b32 v134, v134, v134, s10
	ds_write_b32 v131, v132 offset:34960
	ds_write_b32 v131, v134 offset:53392
	v_mul_f32_e32 v132, v124, v116
	v_mul_f32_e32 v133, v125, v118
	v_mul_f32_e32 v134, v126, v116
	v_mul_f32_e32 v135, v127, v118
	v_cvt_pk_bf16_f32 v132, v132, v133
	v_cvt_pk_bf16_f32 v134, v134, v135
	v_alignbit_b32 v132, v132, v132, s10
	v_alignbit_b32 v134, v134, v134, s10
	ds_write_b32 v131, v132 offset:35104
	ds_write_b32 v131, v134 offset:53536
	v_mul_f32_e32 v132, v124, v117
	v_mul_f32_e32 v133, v125, v119
	v_mul_f32_e32 v134, v126, v117
	v_mul_f32_e32 v135, v127, v119
	v_cvt_pk_bf16_f32 v132, v132, v133
	v_cvt_pk_bf16_f32 v134, v134, v135
	v_alignbit_b32 v132, v132, v132, s10
	v_alignbit_b32 v134, v134, v134, s10
	ds_write_b32 v131, v132 offset:35248
	ds_write_b32 v131, v134 offset:53680
	v_mul_f32_e32 v132, v124, v112
	v_mul_f32_e32 v133, v125, v114
	v_mul_f32_e32 v134, v126, v112
	v_mul_f32_e32 v135, v127, v114
	v_cvt_pk_bf16_f32 v132, v132, v133
	v_cvt_pk_bf16_f32 v134, v134, v135
	v_alignbit_b32 v132, v132, v132, s10
	v_alignbit_b32 v134, v134, v134, s10
	ds_write_b32 v131, v132 offset:35392
	ds_write_b32 v131, v134 offset:53824
	v_mul_f32_e32 v132, v124, v113
	v_mul_f32_e32 v133, v125, v115
	v_mul_f32_e32 v134, v126, v113
	v_mul_f32_e32 v135, v127, v115
	v_cvt_pk_bf16_f32 v132, v132, v133
	v_cvt_pk_bf16_f32 v134, v134, v135
	v_alignbit_b32 v132, v132, v132, s10
	v_alignbit_b32 v134, v134, v134, s10
	ds_write_b32 v131, v132 offset:35536
	ds_write_b32 v131, v134 offset:53968
	v_mul_f32_e32 v132, v124, v108
	v_mul_f32_e32 v133, v125, v110
	v_mul_f32_e32 v134, v126, v108
	v_mul_f32_e32 v135, v127, v110
	v_cvt_pk_bf16_f32 v132, v132, v133
	v_cvt_pk_bf16_f32 v134, v134, v135
	v_alignbit_b32 v132, v132, v132, s10
	v_alignbit_b32 v134, v134, v134, s10
	ds_write_b32 v131, v132 offset:35680
	ds_write_b32 v131, v134 offset:54112
	v_mul_f32_e32 v132, v124, v109
	v_mul_f32_e32 v133, v125, v111
	v_mul_f32_e32 v134, v126, v109
	v_mul_f32_e32 v135, v127, v111
	v_cvt_pk_bf16_f32 v132, v132, v133
	v_cvt_pk_bf16_f32 v134, v134, v135
	v_alignbit_b32 v132, v132, v132, s10
	v_alignbit_b32 v134, v134, v134, s10
	ds_write_b32 v131, v132 offset:35824
	ds_write_b32 v131, v134 offset:54256
	v_lshlrev_b32_e32 v127, 16, v104
	v_lshlrev_b32_e32 v126, 16, v92
	v_and_b32_e32 v125, 0xffff0000, v104
	v_and_b32_e32 v124, 0xffff0000, v92
	v_lshlrev_b32_e32 v129, 16, v105
	v_lshlrev_b32_e32 v128, 16, v93
	v_and_b32_e32 v131, 0xffff0000, v105
	v_and_b32_e32 v130, 0xffff0000, v93
	v_lshlrev_b32_e32 v133, 16, v106
	v_lshlrev_b32_e32 v132, 16, v94
	v_and_b32_e32 v135, 0xffff0000, v106
	v_and_b32_e32 v134, 0xffff0000, v94
	v_lshlrev_b32_e32 v137, 16, v107
	v_lshlrev_b32_e32 v136, 16, v95
	v_and_b32_e32 v139, 0xffff0000, v107
	v_and_b32_e32 v138, 0xffff0000, v95
.LBB0_361:
	s_cmp_lg_u64 s[4:5], 0
	s_cselect_b32 s10, 0, 16
	v_mov_b32_e32 v109, s65
	v_mad_u32_u24 v109, v206, s74, v109
	v_min_u32_e32 v110, v142, v143
	v_lshl_add_u32 v110, v110, 1, v109
	s_waitcnt lgkmcnt(0)
	v_mul_f32_e32 v108, v141, v126
	v_mul_f32_e32 v111, v0, v127
	v_cvt_pk_bf16_f32 v108, v108, v111
	v_alignbit_b32 v108, v108, v108, s10
	ds_write_b32 v110, v108 offset:0
	v_mul_f32_e32 v108, v141, v124
	v_mul_f32_e32 v111, v0, v125
	v_cvt_pk_bf16_f32 v108, v108, v111
	v_alignbit_b32 v108, v108, v108, s10
	ds_write_b32 v110, v108 offset:144
	v_mul_f32_e32 v108, v141, v128
	v_mul_f32_e32 v111, v0, v129
	v_cvt_pk_bf16_f32 v108, v108, v111
	v_alignbit_b32 v108, v108, v108, s10
	ds_write_b32 v110, v108 offset:288
	v_mul_f32_e32 v108, v141, v130
	v_mul_f32_e32 v111, v0, v131
	v_cvt_pk_bf16_f32 v108, v108, v111
	v_alignbit_b32 v108, v108, v108, s10
	ds_write_b32 v110, v108 offset:432
	v_mul_f32_e32 v108, v141, v132
	v_mul_f32_e32 v111, v0, v133
	v_cvt_pk_bf16_f32 v108, v108, v111
	v_alignbit_b32 v108, v108, v108, s10
	ds_write_b32 v110, v108 offset:576
	v_mul_f32_e32 v108, v141, v134
	v_mul_f32_e32 v111, v0, v135
	v_cvt_pk_bf16_f32 v108, v108, v111
	v_alignbit_b32 v108, v108, v108, s10
	ds_write_b32 v110, v108 offset:720
	v_mul_f32_e32 v108, v141, v136
	v_mul_f32_e32 v111, v0, v137
	v_cvt_pk_bf16_f32 v108, v108, v111
	v_alignbit_b32 v108, v108, v108, s10
	ds_write_b32 v110, v108 offset:864
	v_mul_f32_e32 v108, v141, v138
	v_mul_f32_e32 v111, v0, v139
	v_cvt_pk_bf16_f32 v108, v108, v111
	v_alignbit_b32 v108, v108, v108, s10
	ds_write_b32 v110, v108 offset:1008
	v_and_b32_e32 v118, 48, v3
	v_add_u32_e32 v0, 0, v118
	v_or_b32_e32 v108, s92, v206
	s_waitcnt lgkmcnt(0)
	s_barrier
	s_add_i32 s10, s94, 1
	s_cmp_ge_u32 s10, s85
	s_cbranch_scc1 .Lgpf_skip
	s_and_b64 vcc, exec, s[6:7]
	s_cbranch_vccz .Lgpf_skip
	s_lshl_b32 s10, s10, 6
	v_add_u32_e32 v228, s10, v140
	v_xad_u32 v229, v228, -1, s80
	v_cndmask_b32_e64 v229, v229, v228, s[4:5]
	v_add_u32_e32 v228, 1, v228
	v_xad_u32 v230, v228, -1, s80
	v_cndmask_b32_e64 v228, v230, v228, s[4:5]
	v_min_i32_e32 v228, v229, v228
	v_add_u32_e32 v228, v228, v177
	v_mad_i64_i32 v[230:231], vcc, v228, s60, v[182:183]
	v_lshlrev_b32_e32 v228, 4, v205
	v_and_b32_e32 v228, 0xf0, v228
	v_mov_b32_e32 v229, 0
	v_lshl_add_u64 v[230:231], v[230:231], 0, v[228:229]
	global_load_dwordx4 v[84:87], v[230:231], off
	global_load_dwordx4 v[88:91], v[230:231], off offset:2048
	v_lshl_add_u64 v[232:233], v[230:231], 0, s[40:41]
	global_load_dwordx4 v[92:95], v[232:233], off offset:-4096
	global_load_dwordx4 v[96:99], v[232:233], off offset:512
	global_load_dwordx4 v[100:103], v[232:233], off offset:2560
	v_lshl_add_u64 v[234:235], v[232:233], 0, s[40:41]
	global_load_dwordx4 v[104:107], v[234:235], off offset:-3584
	v_or_b32_e32 v228, s10, v3
	v_xad_u32 v230, v228, -1, s80
	v_cndmask_b32_e64 v228, v230, v228, s[4:5]
	v_add_u32_e32 v228, v228, v177
	v_mov_b64_e32 v[232:233], s[36:37]
	v_mad_i64_i32 v[232:233], vcc, v228, s60, v[232:233]
	v_mov_b32_e32 v234, v2
	v_mov_b32_e32 v235, 0
	v_lshl_add_u64 v[232:233], v[232:233], 0, v[234:235]
	v_mov_b32_e32 v234, v180
	v_lshl_add_u64 v[232:233], v[232:233], 0, v[234:235]
	v_lshl_add_u64 v[232:233], v[232:233], 0, s[40:41]
	global_load_ushort v181, v[232:233], off
	global_load_ushort v186, v[232:233], off offset:32
.Lgpf_skip:
	v_mad_u64_u32 v[116:117], s[10:11], v108, s71, v[0:1]
	ds_read_b128 v[108:111], v116 offset:17408
	v_or_b32_e32 v119, s93, v206
	v_mul_lo_u32 v112, v119, s71
	v_add3_u32 v117, s91, v112, v118
	ds_read_b128 v[112:115], v116 offset:17472
	ds_read_b128 v[120:123], v117
	ds_read_b128 v[124:127], v117 offset:64
	s_waitcnt lgkmcnt(1)
	v_mfma_f32_16x16x32_bf16 v[108:111], v[108:111], v[120:123], 0
	ds_read_b128 v[120:123], v116 offset:17536
	v_lshrrev_b32_e32 v207, 4, v3
	s_mov_b64 s[12:13], -1
	s_waitcnt lgkmcnt(1)
	v_mfma_f32_16x16x32_bf16 v[108:111], v[112:115], v[124:127], v[108:111]
	ds_read_b128 v[112:115], v116 offset:17600
	ds_read_b128 v[124:127], v117 offset:128
	ds_read_b128 v[128:131], v117 offset:192
	v_add_u32_e32 v117, s81, v118
	v_lshlrev_b32_e32 v116, 2, v207
	s_waitcnt lgkmcnt(1)
	v_mfma_f32_16x16x32_bf16 v[108:111], v[120:123], v[124:127], v[108:111]
	v_cndmask_b32_e64 v122, 0, 1, s[18:19]
	v_or_b32_e32 v120, s92, v116
	v_cmp_ne_u32_e64 s[10:11], 1, v122
	s_waitcnt lgkmcnt(0)
	v_mfma_f32_16x16x32_bf16 v[112:115], v[112:115], v[128:131], v[108:111]
	s_andn2_b64 vcc, exec, s[18:19]
	s_nop 1
	v_lshlrev_b32_e32 v108, 2, v119
	v_add_u32_e32 v109, s81, v108
	v_add_u32_e32 v108, s82, v108
	v_lshl_add_u32 v110, s92, 2, v117
	ds_read_b32 v121, v109
	ds_read_b32 v118, v108
	ds_read_b128 v[108:111], v110
	s_waitcnt lgkmcnt(0)
	v_sub_f32_e32 v108, v121, v108
	v_mul_f32_e32 v122, 0x3fb8aa3b, v108
	s_cbranch_vccnz .LBB0_363
	v_exp_f32_e32 v108, v122
	v_cmp_le_i32_e32 vcc, v120, v119
	s_mov_b64 s[12:13], 0
	v_mul_f32_e32 v108, v112, v108
	v_cndmask_b32_e32 v108, 0, v108, vcc

.LBB0_403:
	v_lshrrev_b32_e32 v210, 3, v206
	v_bitop3_b32 v108, v210, v207, s86 bitop3:0x36
	v_mul_u32_u24_e32 v213, 0x90, v206
	s_add_i32 s12, 0, 0x1e600
	v_or_b32_e32 v0, s86, v210
	s_add_i32 s10, 0, 0x21e00
	v_lshlrev_b32_e32 v141, 3, v108
	v_mul_u32_u24_e32 v108, 40, v206
	v_bitop3_b32 v109, v207, v0, 4 bitop3:0x36
	v_add3_u32 v120, s12, v213, v209
	s_waitcnt lgkmcnt(0)
	s_barrier
	v_add3_u32 v108, s10, v208, v108
	v_mul_lo_u32 v113, v118, s76
	v_bitop3_b32 v110, v207, v0, 8 bitop3:0x36
	ds_read2_b64 v[124:127], v108 offset1:80
	ds_read2_b64 v[128:131], v108 offset0:160 offset1:240
	v_lshlrev_b32_e32 v148, 3, v109
	v_add_u32_e32 v108, 0x1000, v120
	v_add_u32_e32 v121, s65, v113
	v_lshlrev_b32_e32 v112, 3, v110
	ds_read2_b64 v[132:135], v108 offset0:64 offset1:68
	v_add_u32_e32 v108, v121, v141
	v_add_u32_e32 v110, v121, v148
	ds_read_b64 v[150:151], v120 offset:2304
	ds_read_b64 v[108:109], v108
	ds_read_b64 v[110:111], v110
	ds_read_b64 v[152:153], v120 offset:6976
	s_waitcnt lgkmcnt(2)
	v_mfma_f32_16x16x16_bf16 v[116:119], v[124:125], v[108:109], 0
	v_add_u32_e32 v114, v121, v112
	s_waitcnt lgkmcnt(1)
	v_lshlrev_b32_e32 v108, 16, v110
	v_and_b32_e32 v109, 0xffff0000, v110
	s_nop 3
	v_cvt_pk_bf16_f32 v142, v116, v117
	v_cvt_pk_bf16_f32 v143, v118, v119
	v_lshlrev_b32_e32 v110, 16, v111
	v_and_b32_e32 v111, 0xffff0000, v111
	ds_read_b64 v[114:115], v114
	v_bitop3_b32 v0, v207, v0, 12 bitop3:0x36
	v_mfma_f32_16x16x16_bf16 v[108:111], v[150:151], v[142:143], v[108:111]
	v_lshlrev_b32_e32 v0, 3, v0
	v_add_u32_e32 v149, 0, v113
	v_add_u32_e32 v121, v121, v0
	v_add_u32_e32 v112, v149, v112
	v_add_u32_e32 v0, v149, v0
	s_nop 2
	v_cvt_pk_bf16_f32 v108, v108, v109
	v_cvt_pk_bf16_f32 v109, v110, v111
	ds_read_b64 v[144:145], v121
	ds_read_b64 v[154:155], v0 offset:34816
	ds_read_b64 v[156:157], v112 offset:34816
	v_mfma_f32_16x16x16_bf16 v[108:111], v[126:127], v[108:109], 0
	s_waitcnt lgkmcnt(3)
	v_lshlrev_b32_e32 v112, 16, v114
	v_and_b32_e32 v113, 0xffff0000, v114
	v_lshlrev_b32_e32 v114, 16, v115
	v_and_b32_e32 v115, 0xffff0000, v115
	v_add_u32_e32 v0, 0x1800, v120
	ds_read2_b64 v[136:139], v0 offset0:96 offset1:100
	v_mfma_f32_16x16x16_bf16 v[112:115], v[132:133], v[142:143], v[112:115]
	v_cvt_pk_bf16_f32 v146, v108, v109
	v_cvt_pk_bf16_f32 v147, v110, v111
	v_add_u32_e32 v0, v149, v141
	v_mul_u32_u24_e32 v211, 0x440, v207
	v_mfma_f32_16x16x16_bf16 v[112:115], v[134:135], v[146:147], v[112:115]
	v_lshlrev_b32_e32 v212, 1, v206
	s_add_i32 s13, s94, 1
	s_cmp_lt_u32 s13, s85
	s_nop 4
	v_cvt_pk_bf16_f32 v112, v112, v113
	v_cvt_pk_bf16_f32 v113, v114, v115
	s_waitcnt lgkmcnt(3)
	v_lshlrev_b32_e32 v114, 16, v145
	v_and_b32_e32 v115, 0xffff0000, v145
	v_mfma_f32_16x16x16_bf16 v[120:123], v[128:129], v[112:113], 0
	v_lshlrev_b32_e32 v112, 16, v144
	v_and_b32_e32 v113, 0xffff0000, v144
	s_waitcnt lgkmcnt(0)
	s_nop 0
	v_mfma_f32_16x16x16_bf16 v[112:115], v[136:137], v[142:143], v[112:115]
	s_nop 2
	v_cvt_pk_bf16_f32 v142, v120, v121
	v_cvt_pk_bf16_f32 v143, v122, v123
	v_mfma_f32_16x16x16_bf16 v[112:115], v[138:139], v[146:147], v[112:115]
	s_nop 0
	v_mfma_f32_16x16x16_bf16 v[112:115], v[152:153], v[142:143], v[112:115]
	ds_read_b64 v[142:143], v0 offset:34816
	v_add_u32_e32 v0, v149, v148
	ds_read_b64 v[148:149], v0 offset:34816
	s_waitcnt lgkmcnt(1)
	v_mfma_f32_16x16x16_bf16 v[142:145], v[124:125], v[142:143], 0
	s_waitcnt lgkmcnt(0)
	v_lshlrev_b32_e32 v146, 16, v148
	v_and_b32_e32 v147, 0xffff0000, v148
	s_nop 4
	v_cvt_pk_bf16_f32 v158, v142, v143
	v_cvt_pk_bf16_f32 v159, v144, v145
	v_lshlrev_b32_e32 v148, 16, v149
	v_and_b32_e32 v149, 0xffff0000, v149
	v_cvt_pk_bf16_f32 v112, v112, v113
	v_cvt_pk_bf16_f32 v113, v114, v115
	v_mfma_f32_16x16x16_bf16 v[146:149], v[150:151], v[158:159], v[146:149]
	v_cvt_pk_bf16_f32 v0, -v142, s0
	v_mfma_f32_16x16x16_bf16 v[112:115], v[130:131], v[112:113], 0
	s_nop 5
	v_cvt_pk_bf16_f32 v124, v146, v147
	v_cvt_pk_bf16_f32 v125, v148, v149
	v_lshlrev_b32_e32 v146, 16, v156
	v_and_b32_e32 v147, 0xffff0000, v156
	v_mfma_f32_16x16x16_bf16 v[124:127], v[126:127], v[124:125], 0
	v_lshlrev_b32_e32 v148, 16, v157
	v_and_b32_e32 v149, 0xffff0000, v157
	s_nop 1
	v_mfma_f32_16x16x16_bf16 v[146:149], v[132:133], v[158:159], v[146:149]
	s_nop 2
	v_cvt_pk_bf16_f32 v150, v124, v125
	v_cvt_pk_bf16_f32 v151, v126, v127
	s_nop 1
	v_mfma_f32_16x16x16_bf16 v[132:135], v[134:135], v[150:151], v[146:149]
	s_nop 2
	v_lshlrev_b32_e32 v146, 16, v154
	v_and_b32_e32 v147, 0xffff0000, v154
	v_lshlrev_b32_e32 v148, 16, v155
	v_and_b32_e32 v149, 0xffff0000, v155
	s_nop 0
	v_cvt_pk_bf16_f32 v132, v132, v133
	v_cvt_pk_bf16_f32 v133, v134, v135
	v_mfma_f32_16x16x16_bf16 v[146:149], v[136:137], v[158:159], v[146:149]
	s_nop 0
	v_mfma_f32_16x16x16_bf16 v[132:135], v[128:129], v[132:133], 0
	v_mfma_f32_16x16x16_bf16 v[136:139], v[138:139], v[150:151], v[146:149]
	s_nop 6
	v_cvt_pk_bf16_f32 v128, v132, v133
	v_cvt_pk_bf16_f32 v129, v134, v135
	s_nop 1
	v_mfma_f32_16x16x16_bf16 v[136:139], v[152:153], v[128:129], v[136:139]
	s_nop 7
	v_cvt_pk_bf16_f32 v128, v136, v137
	v_cvt_pk_bf16_f32 v129, v138, v139
	v_add3_u32 v136, s95, v211, v212
	ds_write_b16 v136, v0
	v_mfma_f32_16x16x16_bf16 v[128:131], v[130:131], v[128:129], 0
	v_cvt_pk_bf16_f32 v0, -v124, s0
	ds_write_b16 v136, v0 offset:4352
	v_cvt_pk_bf16_f32 v0, -v132, s0
	ds_write_b16 v136, v0 offset:8704
	s_nop 3
	v_cvt_pk_bf16_f32 v0, -v128, s0
	ds_write_b16 v136, v0 offset:13056
	v_cvt_pk_bf16_f32 v0, -v143, s0
	ds_write_b16 v136, v0 offset:272
	v_cvt_pk_bf16_f32 v0, -v125, s0
	ds_write_b16 v136, v0 offset:4624
	v_cvt_pk_bf16_f32 v0, -v133, s0
	ds_write_b16 v136, v0 offset:8976
	v_cvt_pk_bf16_f32 v0, -v129, s0
	ds_write_b16 v136, v0 offset:13328
	v_cvt_pk_bf16_f32 v0, -v144, s0
	ds_write_b16 v136, v0 offset:544
	v_cvt_pk_bf16_f32 v0, -v126, s0
	ds_write_b16 v136, v0 offset:4896
	v_cvt_pk_bf16_f32 v0, -v134, s0
	ds_write_b16 v136, v0 offset:9248
	v_cvt_pk_bf16_f32 v0, -v130, s0
	ds_write_b16 v136, v0 offset:13600
	v_cvt_pk_bf16_f32 v0, -v145, s0
	ds_write_b16 v136, v0 offset:816
	v_cvt_pk_bf16_f32 v0, -v127, s0
	ds_write_b16 v136, v0 offset:5168
	v_cvt_pk_bf16_f32 v0, -v135, s0
	ds_write_b16 v136, v0 offset:9520
	v_cvt_pk_bf16_f32 v0, -v131, s0
	ds_write_b16 v136, v0 offset:13872
	s_waitcnt lgkmcnt(0)
	s_barrier
	s_cbranch_scc0 .LBB0_409
	s_and_b64 vcc, exec, s[6:7]
	s_cbranch_vccnz .LBB0_409
	s_lshl_b32 s48, s13, 6
	v_add_u32_e32 v0, s48, v140
	v_xad_u32 v84, v0, -1, s80
	v_cndmask_b32_e64 v84, v84, v0, s[4:5]
	v_add_u32_e32 v0, 1, v0
	v_xad_u32 v85, v0, -1, s80
	v_cndmask_b32_e64 v0, v85, v0, s[4:5]
	v_min_i32_e32 v181, v84, v0
	v_add_u32_e32 v0, v181, v177
	v_mad_i64_i32 v[84:85], s[10:11], v0, s60, v[182:183]
	v_lshlrev_b32_e32 v0, 4, v205
	v_and_b32_e32 v0, 0xf0, v0
	v_lshl_add_u64 v[186:187], v[84:85], 0, v[0:1]
	s_and_b64 vcc, exec, s[6:7]
	s_mov_b64 s[10:11], -1
	s_cbranch_vccnz .LBB0_406
	v_add_u32_e32 v0, -2, v181
	v_cmp_gt_u32_e64 s[10:11], s43, v0
	v_add_u32_e32 v0, -1, v181
	s_nop 0
	v_cndmask_b32_e64 v85, 0, -1, s[10:11]
	v_cndmask_b32_e64 v84, 0, v192, s[10:11]
	v_lshl_add_u64 v[92:93], v[186:187], 0, v[84:85]
	global_load_dwordx4 v[84:87], v[92:93], off
	global_load_dwordx4 v[88:91], v[92:93], off offset:2048
	v_add_co_u32_e32 v92, vcc, 0x1000, v92
	s_waitcnt vmcnt(1)
	v_cndmask_b32_e64 v129, 0, v85, s[10:11]
	v_addc_co_u32_e32 v93, vcc, 0, v93, vcc
	global_load_dwordx4 v[92:95], v[92:93], off
	v_cmp_gt_u32_e32 vcc, s43, v0
	v_cndmask_b32_e64 v128, 0, v84, s[10:11]
	v_cndmask_b32_e64 v131, 0, v87, s[10:11]
	v_cndmask_b32_e64 v85, 0, -1, vcc
	v_cndmask_b32_e32 v84, 0, v193, vcc
	v_cndmask_b32_e64 v130, 0, v86, s[10:11]
	s_waitcnt vmcnt(1)
	v_cndmask_b32_e64 v127, 0, v91, s[10:11]
	v_cndmask_b32_e64 v126, 0, v90, s[10:11]
	v_cndmask_b32_e64 v125, 0, v89, s[10:11]
	v_cndmask_b32_e64 v124, 0, v88, s[10:11]
	v_add_u32_e32 v0, 1, v181
	s_waitcnt vmcnt(0)
	v_cndmask_b32_e64 v133, 0, v93, s[10:11]
	v_cndmask_b32_e64 v132, 0, v92, s[10:11]
	v_lshl_add_u64 v[92:93], v[186:187], 0, v[84:85]
	v_cndmask_b32_e64 v135, 0, v95, s[10:11]
	v_cndmask_b32_e64 v134, 0, v94, s[10:11]
	global_load_dwordx4 v[84:87], v[92:93], off
	global_load_dwordx4 v[88:91], v[92:93], off offset:2048
	v_add_co_u32_e64 v92, s[10:11], s59, v92
	s_waitcnt vmcnt(1)
	v_cndmask_b32_e32 v143, 0, v87, vcc
	v_addc_co_u32_e64 v93, s[10:11], 0, v93, s[10:11]
	global_load_dwordx4 v[92:95], v[92:93], off
	v_cndmask_b32_e32 v142, 0, v86, vcc
	v_cndmask_b32_e32 v141, 0, v85, vcc
	v_cndmask_b32_e32 v140, 0, v84, vcc
	s_waitcnt vmcnt(1)
	v_cndmask_b32_e32 v139, 0, v91, vcc
	v_cndmask_b32_e32 v138, 0, v90, vcc
	v_cndmask_b32_e32 v137, 0, v89, vcc
	v_cndmask_b32_e32 v136, 0, v88, vcc
	global_load_dwordx4 v[84:87], v[186:187], off
	global_load_dwordx4 v[88:91], v[186:187], off offset:2048
	s_waitcnt vmcnt(2)
	v_cndmask_b32_e32 v144, 0, v92, vcc
	v_add_co_u32_e64 v92, s[10:11], s59, v186
	v_cndmask_b32_e32 v145, 0, v93, vcc
	s_nop 0
	v_addc_co_u32_e64 v93, s[10:11], 0, v187, s[10:11]
	v_cndmask_b32_e32 v147, 0, v95, vcc
	v_cndmask_b32_e32 v146, 0, v94, vcc
	global_load_dwordx4 v[92:95], v[92:93], off
	v_cmp_gt_u32_e32 vcc, s43, v181
	s_waitcnt vmcnt(2)
	s_nop 0
	v_cndmask_b32_e32 v87, 0, v87, vcc
	v_cndmask_b32_e32 v86, 0, v86, vcc
	v_cndmask_b32_e32 v85, 0, v85, vcc
	v_cndmask_b32_e32 v84, 0, v84, vcc
	s_waitcnt vmcnt(1)
	v_cndmask_b32_e32 v91, 0, v91, vcc
	v_cndmask_b32_e32 v90, 0, v90, vcc
	v_cndmask_b32_e32 v89, 0, v89, vcc
	v_cndmask_b32_e32 v88, 0, v88, vcc
	s_waitcnt vmcnt(0)
	v_cndmask_b32_e32 v95, 0, v95, vcc
	v_cndmask_b32_e32 v94, 0, v94, vcc
	v_cndmask_b32_e32 v93, 0, v93, vcc
	v_cndmask_b32_e32 v92, 0, v92, vcc
	v_cmp_gt_u32_e32 vcc, s43, v0
	s_nop 1
	v_cndmask_b32_e32 v0, 0, v194, vcc
	v_lshl_add_u64 v[104:105], v[186:187], 0, v[0:1]
	global_load_dwordx4 v[96:99], v[104:105], off
	global_load_dwordx4 v[100:103], v[104:105], off offset:2048
	v_add_co_u32_e64 v104, s[10:11], s59, v104
	v_add_u32_e32 v0, 2, v181
	s_nop 0
	v_addc_co_u32_e64 v105, s[10:11], 0, v105, s[10:11]
	global_load_dwordx4 v[104:107], v[104:105], off
	s_waitcnt vmcnt(2)
	v_cndmask_b32_e32 v99, 0, v99, vcc
	v_cndmask_b32_e32 v98, 0, v98, vcc
	v_cndmask_b32_e32 v97, 0, v97, vcc
	v_cndmask_b32_e32 v96, 0, v96, vcc
	s_waitcnt vmcnt(1)
	v_cndmask_b32_e32 v103, 0, v103, vcc
	v_cndmask_b32_e32 v102, 0, v102, vcc
	v_cndmask_b32_e32 v101, 0, v101, vcc
	v_cndmask_b32_e32 v100, 0, v100, vcc
	s_waitcnt vmcnt(0)
	v_cndmask_b32_e32 v107, 0, v107, vcc
	v_cndmask_b32_e32 v106, 0, v106, vcc
	v_cndmask_b32_e32 v105, 0, v105, vcc
	v_cndmask_b32_e32 v104, 0, v104, vcc
	v_cmp_gt_u32_e32 vcc, s43, v0
	s_nop 1
	v_cndmask_b32_e32 v0, 0, v195, vcc
	v_lshl_add_u64 v[156:157], v[186:187], 0, v[0:1]
	global_load_dwordx4 v[148:151], v[156:157], off
	global_load_dwordx4 v[152:155], v[156:157], off offset:2048
	v_add_co_u32_e64 v156, s[10:11], s59, v156
	v_add_u32_e32 v0, 3, v181
	s_nop 0
	v_addc_co_u32_e64 v157, s[10:11], 0, v157, s[10:11]
	global_load_dwordx4 v[160:163], v[156:157], off
	s_waitcnt vmcnt(2)
	v_cndmask_b32_e32 v159, 0, v151, vcc
	v_cndmask_b32_e32 v158, 0, v150, vcc
	v_cndmask_b32_e32 v157, 0, v149, vcc
	v_cndmask_b32_e32 v156, 0, v148, vcc
	s_waitcnt vmcnt(1)
	v_cndmask_b32_e32 v155, 0, v155, vcc
	v_cndmask_b32_e32 v154, 0, v154, vcc
	v_cndmask_b32_e32 v153, 0, v153, vcc
	v_cndmask_b32_e32 v152, 0, v152, vcc
	s_waitcnt vmcnt(0)
	v_cndmask_b32_e32 v151, 0, v163, vcc
	v_cndmask_b32_e32 v150, 0, v162, vcc
	v_cndmask_b32_e32 v149, 0, v161, vcc
	v_cndmask_b32_e32 v148, 0, v160, vcc
	v_cmp_gt_u32_e32 vcc, s43, v0
	s_nop 1
	v_cndmask_b32_e32 v0, 0, v196, vcc
	v_lshl_add_u64 v[160:161], v[186:187], 0, v[0:1]
	global_load_dwordx4 v[168:171], v[160:161], off
	global_load_dwordx4 v[164:167], v[160:161], off offset:2048
	v_add_co_u32_e64 v160, s[10:11], s59, v160
	s_waitcnt vmcnt(1)
	v_cndmask_b32_e32 v171, 0, v171, vcc
	v_addc_co_u32_e64 v161, s[10:11], 0, v161, s[10:11]
	global_load_dwordx4 v[160:163], v[160:161], off
	v_cndmask_b32_e32 v170, 0, v170, vcc
	v_cndmask_b32_e32 v169, 0, v169, vcc
	v_cndmask_b32_e32 v168, 0, v168, vcc
	s_waitcnt vmcnt(1)
	v_cndmask_b32_e32 v167, 0, v167, vcc
	v_cndmask_b32_e32 v166, 0, v166, vcc
	v_cndmask_b32_e32 v165, 0, v165, vcc
	v_cndmask_b32_e32 v164, 0, v164, vcc
	s_mov_b64 s[10:11], 0
	s_waitcnt vmcnt(0)
	v_cndmask_b32_e32 v163, 0, v163, vcc
	v_cndmask_b32_e32 v162, 0, v162, vcc
	v_cndmask_b32_e32 v161, 0, v161, vcc
	v_cndmask_b32_e32 v160, 0, v160, vcc

.LBB0_1015:
	s_xor_b64 s[18:19], s[4:5], -1
	s_and_b64 s[10:11], exec, s[4:5]
	s_cselect_b32 s46, 0x800, s40
	v_lshlrev_b32_e32 v37, 11, v36
	v_add_u32_e32 v37, 0x1000, v37
	v_lshlrev_b32_e32 v36, 8, v36
	s_lshr_b32 s45, s46, 6
	s_add_i32 s46, s46, -1
	v_cmp_eq_u32_e32 vcc, 0, v34
	v_cndmask_b32_e64 v74, v36, v37, s[4:5]
	s_and_b64 s[4:5], vcc, exec
	s_cselect_b32 s4, 0, s46
	s_cselect_b32 s48, 1, -1
	v_add_u32_e32 v36, s4, v74
	v_ashrrev_i32_e32 v90, 7, v33
	v_mul_hi_u32 v37, v36, s39
	v_mul_lo_u32 v36, v36, s39
	s_lshl_b32 s47, s48, 4
	v_and_b32_e32 v88, 0x7f, v33
	v_lshlrev_b32_e32 v117, 7, v35
	s_waitcnt lgkmcnt(0)
	v_lshl_add_u64 v[36:37], s[8:9], 0, v[36:37]
	v_mul_lo_u32 v96, s47, v90
	s_mul_i32 s34, s48, 0x1400
	s_waitcnt vmcnt(47)
	v_or_b32_e32 v47, 0xc00, v117
	v_mad_i64_i32 v[36:37], s[4:5], v96, s39, v[36:37]
	v_lshlrev_b32_e32 v44, 1, v88
	s_ashr_i32 s35, s34, 31
	v_lshl_add_u64 v[36:37], v[36:37], 0, v[44:45]
	v_lshlrev_b32_e32 v38, 8, v35
	v_mov_b32_e32 v39, v45
	v_lshlrev_b32_e32 v50, 1, v47
	s_waitcnt vmcnt(5)
	v_mov_b32_e32 v51, v45
	s_lshl_b64 s[36:37], s[34:35], 1
	v_lshl_add_u64 v[40:41], v[36:37], 0, v[38:39]
	v_lshl_add_u64 v[58:59], v[36:37], 0, v[50:51]
	v_lshl_add_u64 v[36:37], v[36:37], 0, s[36:37]
	v_lshl_add_u64 v[60:61], v[36:37], 0, v[38:39]
	v_lshl_add_u64 v[64:65], v[36:37], 0, v[50:51]
	v_lshl_add_u64 v[36:37], v[36:37], 0, s[36:37]
	v_lshlrev_b32_e32 v42, 11, v34
	v_mov_b32_e32 v43, v45
	s_waitcnt vmcnt(4)
	v_lshl_add_u64 v[66:67], v[36:37], 0, v[38:39]
	v_lshl_add_u64 v[56:57], v[40:41], 0, v[42:43]
	v_lshl_add_u64 v[62:63], v[60:61], 0, v[42:43]
	v_lshl_add_u64 v[80:81], v[66:67], 0, v[42:43]
	global_load_ushort v75, v[40:41], off
	global_load_ushort v52, v[56:57], off offset:2048
	global_load_ushort v76, v[58:59], off
	global_load_ushort v77, v[60:61], off
	global_load_ushort v47, v[62:63], off offset:2048
	global_load_ushort v78, v[64:65], off
	global_load_ushort v79, v[66:67], off
	global_load_ushort v54, v[80:81], off offset:2048
	v_lshl_add_u64 v[40:41], v[36:37], 0, v[50:51]
	v_lshl_add_u64 v[36:37], v[36:37], 0, s[36:37]
	v_lshl_add_u64 v[56:57], v[36:37], 0, v[38:39]
	v_lshl_add_u64 v[60:61], v[36:37], 0, v[50:51]
	v_lshl_add_u64 v[36:37], v[36:37], 0, s[36:37]
	v_lshl_add_u64 v[62:63], v[36:37], 0, v[38:39]
	v_lshl_add_u64 v[58:59], v[56:57], 0, v[42:43]
	global_load_ushort v80, v[40:41], off
	global_load_ushort v81, v[56:57], off
	global_load_ushort v49, v[58:59], off offset:2048
	global_load_ushort v82, v[60:61], off
	global_load_ushort v83, v[62:63], off
	v_lshl_add_u64 v[40:41], v[62:63], 0, v[42:43]
	global_load_ushort v56, v[40:41], off offset:2048
	v_lshl_add_u64 v[40:41], v[36:37], 0, v[50:51]
	v_lshl_add_u64 v[36:37], v[36:37], 0, s[36:37]
	v_lshl_add_u64 v[58:59], v[36:37], 0, v[38:39]
	global_load_ushort v84, v[40:41], off
	global_load_ushort v85, v[58:59], off
	v_lshl_add_u64 v[40:41], v[58:59], 0, v[42:43]
	global_load_ushort v53, v[40:41], off offset:2048
	v_lshl_add_u64 v[40:41], v[36:37], 0, v[50:51]
	v_lshl_add_u64 v[36:37], v[36:37], 0, s[36:37]
	global_load_ushort v86, v[40:41], off
	v_lshl_add_u64 v[40:41], v[36:37], 0, v[38:39]
	global_load_ushort v87, v[40:41], off
	v_lshl_add_u64 v[40:41], v[40:41], 0, v[42:43]
	global_load_ushort v58, v[40:41], off offset:2048
	v_lshl_add_u64 v[40:41], v[36:37], 0, v[50:51]
	v_lshl_add_u64 v[36:37], v[36:37], 0, s[36:37]
	global_load_ushort v89, v[40:41], off
	v_lshl_add_u64 v[40:41], v[36:37], 0, v[38:39]
	global_load_ushort v93, v[40:41], off
	v_lshl_add_u64 v[40:41], v[40:41], 0, v[42:43]
	global_load_ushort v55, v[40:41], off offset:2048
	v_lshl_add_u64 v[40:41], v[36:37], 0, v[50:51]
	v_lshl_add_u64 v[36:37], v[36:37], 0, s[36:37]
	global_load_ushort v94, v[40:41], off
	v_lshl_add_u64 v[40:41], v[36:37], 0, v[38:39]
	global_load_ushort v95, v[40:41], off
	v_lshl_add_u64 v[40:41], v[40:41], 0, v[42:43]
	global_load_ushort v64, v[40:41], off offset:2048
	v_lshl_add_u64 v[40:41], v[36:37], 0, v[50:51]
	v_lshl_add_u64 v[36:37], v[36:37], 0, s[36:37]
	global_load_ushort v97, v[40:41], off
	v_lshl_add_u64 v[40:41], v[36:37], 0, v[38:39]
	global_load_ushort v103, v[40:41], off
	v_lshl_add_u64 v[40:41], v[40:41], 0, v[42:43]
	global_load_ushort v57, v[40:41], off offset:2048
	v_lshl_add_u64 v[40:41], v[36:37], 0, v[50:51]
	v_lshl_add_u64 v[36:37], v[36:37], 0, s[36:37]
	global_load_ushort v105, v[40:41], off
	v_lshl_add_u64 v[40:41], v[36:37], 0, v[38:39]
	global_load_ushort v106, v[40:41], off
	v_lshl_add_u64 v[40:41], v[40:41], 0, v[42:43]
	global_load_ushort v68, v[40:41], off offset:2048
	v_lshl_add_u64 v[40:41], v[36:37], 0, v[50:51]
	v_lshl_add_u64 v[36:37], v[36:37], 0, s[36:37]
	global_load_ushort v107, v[40:41], off
	v_lshl_add_u64 v[40:41], v[36:37], 0, v[38:39]
	global_load_ushort v108, v[40:41], off
	v_lshl_add_u64 v[40:41], v[40:41], 0, v[42:43]
	global_load_ushort v59, v[40:41], off offset:2048
	v_lshl_add_u64 v[40:41], v[36:37], 0, v[50:51]
	v_lshl_add_u64 v[36:37], v[36:37], 0, s[36:37]
	global_load_ushort v109, v[40:41], off
	v_lshl_add_u64 v[40:41], v[36:37], 0, v[38:39]
	global_load_ushort v110, v[40:41], off
	v_lshl_add_u64 v[40:41], v[40:41], 0, v[42:43]
	global_load_ushort v70, v[40:41], off offset:2048
	v_lshl_add_u64 v[40:41], v[36:37], 0, v[50:51]
	v_lshl_add_u64 v[36:37], v[36:37], 0, s[36:37]
	global_load_ushort v111, v[40:41], off
	v_lshl_add_u64 v[40:41], v[36:37], 0, v[38:39]
	global_load_ushort v112, v[40:41], off
	v_lshl_add_u64 v[40:41], v[40:41], 0, v[42:43]
	global_load_ushort v65, v[40:41], off offset:2048
	v_lshl_add_u64 v[40:41], v[36:37], 0, v[50:51]
	v_lshl_add_u64 v[36:37], v[36:37], 0, s[36:37]
	global_load_ushort v113, v[40:41], off
	v_lshl_add_u64 v[40:41], v[36:37], 0, v[38:39]
	global_load_ushort v114, v[40:41], off
	v_lshl_add_u64 v[40:41], v[40:41], 0, v[42:43]
	global_load_ushort v72, v[40:41], off offset:2048
	v_lshl_add_u64 v[40:41], v[36:37], 0, v[50:51]
	v_lshl_add_u64 v[36:37], v[36:37], 0, s[36:37]
	v_lshl_add_u64 v[38:39], v[36:37], 0, v[38:39]
	v_lshl_add_u64 v[36:37], v[36:37], 0, v[50:51]
	global_load_ushort v116, v[38:39], off
	global_load_ushort v51, v[36:37], off
	v_lshl_add_u64 v[38:39], v[38:39], 0, v[42:43]
	global_load_ushort v115, v[40:41], off
	global_load_ushort v67, v[38:39], off offset:2048
	v_lshlrev_b32_e32 v37, 10, v34
	v_mul_u32_u24_e32 v34, 0x48, v88
	v_lshlrev_b32_e32 v34, 1, v34
	v_lshlrev_b32_e32 v35, 5, v90
	v_add3_u32 v91, 0, v34, v35
	v_mov_b64_e32 v[34:35], s[8:9]
	v_or_b32_e32 v38, v37, v117
	v_mad_i64_i32 v[34:35], s[4:5], v96, s39, v[34:35]
	v_lshl_add_u64 v[60:61], v[34:35], 0, v[44:45]
	v_lshlrev_b32_e32 v44, 1, v38
	s_ashr_i32 s7, s6, 31
	v_lshl_add_u64 v[34:35], s[8:9], 0, v[44:45]
	s_lshl_b64 s[4:5], s[6:7], 1
	v_lshl_add_u64 v[34:35], v[34:35], 0, s[4:5]
	v_lshlrev_b32_e32 v44, 1, v32
	v_lshl_add_u64 v[62:63], v[34:35], 0, v[44:45]
	v_mul_lo_u32 v34, v90, s27
	v_or_b32_e32 v34, v34, v88
	v_lshlrev_b32_e32 v36, 2, v73
	v_lshl_add_u32 v92, v33, 2, s65
	v_lshlrev_b32_e32 v33, 3, v73
	v_lshl_add_u32 v96, v34, 1, 0
	v_mul_u32_u24_e32 v34, 0x90, v32
	v_mul_lo_u32 v39, v71, s41
	v_or_b32_e32 v90, 2, v36
	v_or_b32_e32 v88, 3, v36
	v_lshlrev_b32_e32 v98, 4, v73
	v_add3_u32 v99, v34, v33, s42
	v_mul_i32_i24_e32 v34, s48, v73
	s_mov_b32 s49, 0
	v_cmp_gt_u32_e64 s[4:5], v36, v32
	v_cmp_lt_u32_e64 s[6:7], v36, v32
	v_cmp_gt_u32_e64 s[8:9], v90, v32
	v_cmp_gt_u32_e64 s[10:11], v88, v32
	v_add3_u32 v100, v39, v33, s43
	v_lshl_add_u32 v101, v34, 2, v74
	v_mad_u32_u24 v102, v32, s44, v33
	v_mad_u32_u24 v104, v32, s44, v98
	v_lshlrev_b32_e32 v44, 1, v117
	v_lshlrev_b32_e32 v66, 1, v37
	s_mov_b32 s99, 0x12000
	v_readfirstlane_b32 s98, v188
	s_mov_b32 s100, 0
	s_lshr_b32 s98, s98, 8
.LBB0_1016:
	s_waitcnt vmcnt(43)
	v_lshlrev_b32_e32 v41, 16, v47
	v_lshlrev_b32_e32 v40, 16, v52
	v_mov_b32_e32 v146, v41
	v_pk_mul_f32 v[146:147], v[146:147], v[40:41]
	v_rcp_f32_e32 v144, v40
	v_rcp_f32_e32 v145, v146
	v_lshlrev_b32_e32 v35, 16, v75
	v_mul_f32_e32 v35, v40, v35
	v_pk_add_f32 v[40:41], v[40:41], 1.0 op_sel_hi:[1,0] neg_lo:[1,0] neg_hi:[1,0]
	v_cvt_pk_bf16_f32 v35, v35, s0
	v_pk_mul_f32 v[40:41], v[40:41], v[144:145]
	v_lshlrev_b32_e32 v39, 16, v77
	s_waitcnt vmcnt(37)
	v_lshlrev_b32_e32 v43, 16, v49
	v_lshlrev_b32_e32 v42, 16, v54
	ds_write_b16 v96, v35
	v_cvt_pk_bf16_f32 v35, v40, s0
	ds_write_b16 v96, v35 offset:17408
	v_mul_f32_e32 v35, v146, v39
	v_pk_mul_f32 v[144:145], v[146:147], v[42:43]
	v_mov_b32_e32 v146, v43
	v_pk_mul_f32 v[146:147], v[144:145], v[146:147]
	v_pk_add_f32 v[140:141], v[42:43], 1.0 op_sel_hi:[1,0] neg_lo:[1,0] neg_hi:[1,0]
	v_rcp_f32_e32 v42, v144
	v_rcp_f32_e32 v43, v146
	v_cvt_pk_bf16_f32 v35, v35, s0
	v_lshlrev_b32_e32 v117, 16, v79
	ds_write_b16 v96, v35 offset:272
	v_cvt_pk_bf16_f32 v35, v41, s0
	s_waitcnt vmcnt(31)
	v_lshlrev_b32_e32 v119, 16, v53
	v_lshlrev_b32_e32 v118, 16, v56
	ds_write_b16 v96, v35 offset:17680
	v_mul_f32_e32 v35, v144, v117
	v_cvt_pk_bf16_f32 v35, v35, s0
	v_pk_mul_f32 v[42:43], v[140:141], v[42:43]
	v_pk_mul_f32 v[140:141], v[146:147], v[118:119]
	v_mov_b32_e32 v144, v119
	v_lshlrev_b32_e32 v148, 16, v81
	ds_write_b16 v96, v35 offset:544
	v_cvt_pk_bf16_f32 v35, v42, s0
	v_pk_mul_f32 v[144:145], v[140:141], v[144:145]
	v_pk_add_f32 v[136:137], v[118:119], 1.0 op_sel_hi:[1,0] neg_lo:[1,0] neg_hi:[1,0]
	ds_write_b16 v96, v35 offset:17952
	v_mul_f32_e32 v35, v146, v148
	v_rcp_f32_e32 v118, v140
	v_rcp_f32_e32 v119, v144
	v_cvt_pk_bf16_f32 v35, v35, s0
	v_lshlrev_b32_e32 v149, 16, v83
	ds_write_b16 v96, v35 offset:816
	v_cvt_pk_bf16_f32 v35, v43, s0
	s_waitcnt vmcnt(25)
	v_lshlrev_b32_e32 v121, 16, v55
	v_lshlrev_b32_e32 v120, 16, v58
	ds_write_b16 v96, v35 offset:18224
	v_mul_f32_e32 v35, v140, v149
	v_cvt_pk_bf16_f32 v35, v35, s0
	v_pk_mul_f32 v[136:137], v[136:137], v[118:119]
	v_pk_mul_f32 v[118:119], v[144:145], v[120:121]
	v_mov_b32_e32 v140, v121
	v_lshlrev_b32_e32 v150, 16, v85
	ds_write_b16 v96, v35 offset:1088
	v_cvt_pk_bf16_f32 v35, v136, s0
	v_pk_mul_f32 v[140:141], v[118:119], v[140:141]
	v_pk_add_f32 v[132:133], v[120:121], 1.0 op_sel_hi:[1,0] neg_lo:[1,0] neg_hi:[1,0]
	ds_write_b16 v96, v35 offset:18496
	v_mul_f32_e32 v35, v144, v150
	v_rcp_f32_e32 v120, v118
	v_rcp_f32_e32 v121, v140
	v_cvt_pk_bf16_f32 v35, v35, s0
	v_lshlrev_b32_e32 v151, 16, v87
	ds_write_b16 v96, v35 offset:1360
	v_cvt_pk_bf16_f32 v35, v137, s0
	s_waitcnt vmcnt(19)
	v_lshlrev_b32_e32 v123, 16, v57
	v_lshlrev_b32_e32 v122, 16, v64
	ds_write_b16 v96, v35 offset:18768
	v_mul_f32_e32 v35, v118, v151
	v_pk_add_f32 v[142:143], v[122:123], 1.0 op_sel_hi:[1,0] neg_lo:[1,0] neg_hi:[1,0]
	v_cvt_pk_bf16_f32 v35, v35, s0
	v_pk_mul_f32 v[132:133], v[132:133], v[120:121]
	v_pk_mul_f32 v[118:119], v[140:141], v[122:123]
	v_mov_b32_e32 v122, v123
	v_lshlrev_b32_e32 v152, 16, v93
	ds_write_b16 v96, v35 offset:1632
	v_cvt_pk_bf16_f32 v35, v132, s0
	v_pk_mul_f32 v[122:123], v[118:119], v[122:123]
	ds_write_b16 v96, v35 offset:19040
	v_mul_f32_e32 v35, v140, v152
	v_rcp_f32_e32 v120, v118
	v_rcp_f32_e32 v121, v122
	v_cvt_pk_bf16_f32 v35, v35, s0
	v_lshlrev_b32_e32 v153, 16, v95
	ds_write_b16 v96, v35 offset:1904
	v_cvt_pk_bf16_f32 v35, v133, s0
	s_waitcnt vmcnt(13)
	v_lshlrev_b32_e32 v125, 16, v59
	v_lshlrev_b32_e32 v124, 16, v68
	ds_write_b16 v96, v35 offset:19312
	v_mul_f32_e32 v35, v118, v153
	v_pk_add_f32 v[138:139], v[124:125], 1.0 op_sel_hi:[1,0] neg_lo:[1,0] neg_hi:[1,0]
	v_cvt_pk_bf16_f32 v35, v35, s0
	v_pk_mul_f32 v[118:119], v[142:143], v[120:121]
	v_pk_mul_f32 v[120:121], v[122:123], v[124:125]
	v_mov_b32_e32 v124, v125
	v_lshlrev_b32_e32 v154, 16, v103
	ds_write_b16 v96, v35 offset:2176
	v_cvt_pk_bf16_f32 v35, v118, s0
	v_pk_mul_f32 v[124:125], v[120:121], v[124:125]
	ds_write_b16 v96, v35 offset:19584
	v_mul_f32_e32 v35, v122, v154
	v_rcp_f32_e32 v122, v120
	v_rcp_f32_e32 v123, v124
	v_cvt_pk_bf16_f32 v35, v35, s0
	v_lshlrev_b32_e32 v155, 16, v106
	ds_write_b16 v96, v35 offset:2448
	v_cvt_pk_bf16_f32 v35, v119, s0
	s_waitcnt vmcnt(7)
	v_lshlrev_b32_e32 v127, 16, v65
	v_lshlrev_b32_e32 v126, 16, v70
	ds_write_b16 v96, v35 offset:19856
	v_mul_f32_e32 v35, v120, v155
	v_pk_add_f32 v[134:135], v[126:127], 1.0 op_sel_hi:[1,0] neg_lo:[1,0] neg_hi:[1,0]
	v_cvt_pk_bf16_f32 v35, v35, s0
	v_pk_mul_f32 v[120:121], v[138:139], v[122:123]
	v_pk_mul_f32 v[122:123], v[124:125], v[126:127]
	v_mov_b32_e32 v126, v127
	v_lshlrev_b32_e32 v156, 16, v108
	ds_write_b16 v96, v35 offset:2720
	v_cvt_pk_bf16_f32 v35, v120, s0
	v_pk_mul_f32 v[126:127], v[122:123], v[126:127]
	ds_write_b16 v96, v35 offset:20128
	v_mul_f32_e32 v35, v124, v156
	v_rcp_f32_e32 v124, v122
	v_rcp_f32_e32 v125, v126
	v_cvt_pk_bf16_f32 v35, v35, s0
	v_lshlrev_b32_e32 v157, 16, v110
	ds_write_b16 v96, v35 offset:2992
	v_cvt_pk_bf16_f32 v35, v121, s0
	s_waitcnt vmcnt(0)
	v_lshlrev_b32_e32 v129, 16, v67
	v_lshlrev_b32_e32 v128, 16, v72
	ds_write_b16 v96, v35 offset:20400
	v_mul_f32_e32 v35, v122, v157
	v_pk_add_f32 v[130:131], v[128:129], 1.0 op_sel_hi:[1,0] neg_lo:[1,0] neg_hi:[1,0]
	v_cvt_pk_bf16_f32 v35, v35, s0
	v_pk_mul_f32 v[122:123], v[134:135], v[124:125]
	v_pk_mul_f32 v[124:125], v[126:127], v[128:129]
	v_mov_b32_e32 v128, v129
	v_lshlrev_b32_e32 v158, 16, v112
	ds_write_b16 v96, v35 offset:3264
	v_cvt_pk_bf16_f32 v35, v122, s0
	v_pk_mul_f32 v[128:129], v[124:125], v[128:129]
	ds_write_b16 v96, v35 offset:20672
	v_mul_f32_e32 v35, v126, v158
	v_rcp_f32_e32 v126, v124
	v_rcp_f32_e32 v127, v128
	v_cvt_pk_bf16_f32 v35, v35, s0
	v_lshlrev_b32_e32 v159, 16, v114
	ds_write_b16 v96, v35 offset:3536
	v_cvt_pk_bf16_f32 v35, v123, s0
	ds_write_b16 v96, v35 offset:20944
	v_mul_f32_e32 v35, v124, v159
	v_cvt_pk_bf16_f32 v35, v35, s0
	v_pk_mul_f32 v[124:125], v[130:131], v[126:127]
	v_lshlrev_b32_e32 v160, 16, v116
	ds_write_b16 v96, v35 offset:3808
	v_cvt_pk_bf16_f32 v35, v124, s0
	v_pk_mul_f32 v[40:41], v[40:41], v[128:129] op_sel_hi:[1,0]
	v_pk_mul_f32 v[42:43], v[42:43], v[128:129] op_sel_hi:[1,0]
	ds_write_b16 v96, v35 offset:21216
	v_mul_f32_e32 v35, v128, v160
	v_cvt_pk_bf16_f32 v40, v40, v41
	v_pk_mul_f32 v[118:119], v[118:119], v[128:129] op_sel_hi:[1,0]
	v_cvt_pk_bf16_f32 v41, v42, v43
	v_pk_mul_f32 v[42:43], v[120:121], v[128:129] op_sel_hi:[1,0]
	v_cvt_pk_bf16_f32 v35, v35, s0
	v_cvt_pk_bf16_f32 v118, v118, v119
	v_cvt_pk_bf16_f32 v119, v42, v43
	v_pk_mul_f32 v[42:43], v[136:137], v[128:129] op_sel_hi:[1,0]
	v_pk_mul_f32 v[120:121], v[128:129], v[122:123] op_sel_hi:[0,1]
	v_pk_mul_f32 v[122:123], v[132:133], v[128:129] op_sel_hi:[1,0]
	ds_write_b16 v96, v35 offset:4080
	v_cvt_pk_bf16_f32 v35, v125, s0
	v_cvt_pk_bf16_f32 v42, v42, v43
	v_cvt_pk_bf16_f32 v43, v122, v123
	v_pk_mul_f32 v[122:123], v[128:129], v[124:125] op_sel_hi:[0,1]
	v_lshl_or_b32 v32, v78, 16, v76
	v_lshl_or_b32 v36, v105, 16, v97
	v_lshl_or_b32 v33, v82, 16, v80
	v_lshl_or_b32 v37, v109, 16, v107
	v_lshl_or_b32 v34, v86, 16, v84
	v_lshl_or_b32 v38, v113, 16, v111
	ds_write_b16 v96, v35 offset:21488
	v_cvt_pk_bf16_f32 v120, v120, v121
	v_cvt_pk_bf16_f32 v121, v122, v123
	v_lshl_or_b32 v35, v94, 16, v89
	v_lshl_or_b32 v39, v51, 16, v115
	ds_write_b128 v91, v[40:43] offset:34816
	ds_write_b128 v91, v[118:121] offset:34832
	ds_write_b128 v91, v[32:35] offset:53248
	ds_write_b128 v91, v[36:39] offset:53264
	ds_write_b32 v92, v128
	s_cmp_eq_u32 s100, 0
	s_cbranch_scc0 .Lhp_afterprep
	s_mov_b32 s100, 1
	s_waitcnt lgkmcnt(0)
	v_add_u32_e32 v96, s99, v96
	v_add_u32_e32 v91, s99, v91
	v_add_u32_e32 v92, s99, v92
	s_cmp_eq_u32 s98, 0
	s_cbranch_scc1 .Lhp_bar
	s_add_i32 s48, s49, 1
	s_cmp_ge_u32 s48, s45
	s_cbranch_scc1 .Lhp_bar
	s_mov_b32 s101, 1
	s_branch .Lhp_issue
.Lhp_afterprep:
	s_cmp_eq_u32 s98, 0
	s_cbranch_scc1 .Lhp_end
	s_add_i32 s48, s49, 2
	s_cmp_ge_u32 s48, s45
	s_cbranch_scc1 .LBB0_1018
	s_mov_b32 s101, 0
.Lhp_issue:
	s_lshl_b32 s52, s48, 6
	s_sub_i32 s53, s46, s52
	s_and_b64 s[50:51], vcc, exec
	s_cselect_b32 s50, s52, s53
	v_add_u32_e32 v32, s50, v74
	v_mad_i64_i32 v[32:33], s[50:51], v32, s39, v[60:61]
	v_mov_b32_e32 v51, v45
	v_lshl_add_u64 v[34:35], v[32:33], 0, v[44:45]
	v_lshl_add_u64 v[38:39], v[32:33], 0, v[50:51]
	v_lshl_add_u64 v[32:33], s[34:35], 1, v[32:33]
	v_lshl_add_u64 v[40:41], v[32:33], 0, v[44:45]
	v_lshl_add_u64 v[54:55], v[32:33], 0, v[50:51]
	v_lshl_add_u64 v[32:33], v[32:33], 0, s[36:37]
	v_mov_b32_e32 v67, v45
	v_lshl_add_u64 v[56:57], v[32:33], 0, v[44:45]
	v_lshl_add_u64 v[36:37], v[34:35], 0, v[66:67]
	v_lshl_add_u64 v[42:43], v[40:41], 0, v[66:67]
	v_lshl_add_u64 v[58:59], v[56:57], 0, v[66:67]
	global_load_ushort v75, v[34:35], off
	global_load_ushort v52, v[36:37], off offset:2048
	global_load_ushort v76, v[38:39], off
	global_load_ushort v77, v[40:41], off
	global_load_ushort v47, v[42:43], off offset:2048
	global_load_ushort v78, v[54:55], off
	global_load_ushort v79, v[56:57], off
	s_nop 0
	global_load_ushort v54, v[58:59], off offset:2048
	v_lshl_add_u64 v[34:35], v[32:33], 0, v[50:51]
	v_lshl_add_u64 v[32:33], v[32:33], 0, s[36:37]
	v_lshl_add_u64 v[36:37], v[32:33], 0, v[44:45]
	v_lshl_add_u64 v[40:41], v[32:33], 0, v[50:51]
	v_lshl_add_u64 v[32:33], v[32:33], 0, s[36:37]
	v_lshl_add_u64 v[42:43], v[32:33], 0, v[44:45]
	v_lshl_add_u64 v[38:39], v[36:37], 0, v[66:67]
	global_load_ushort v80, v[34:35], off
	global_load_ushort v81, v[36:37], off
	global_load_ushort v49, v[38:39], off offset:2048
	global_load_ushort v82, v[40:41], off
	global_load_ushort v83, v[42:43], off
	v_lshl_add_u64 v[34:35], v[42:43], 0, v[66:67]
	global_load_ushort v56, v[34:35], off offset:2048
	v_lshl_add_u64 v[34:35], v[32:33], 0, v[50:51]
	v_lshl_add_u64 v[32:33], v[32:33], 0, s[36:37]
	v_lshl_add_u64 v[36:37], v[32:33], 0, v[44:45]
	global_load_ushort v84, v[34:35], off
	global_load_ushort v85, v[36:37], off
	v_lshl_add_u64 v[34:35], v[36:37], 0, v[66:67]
	global_load_ushort v53, v[34:35], off offset:2048
	v_lshl_add_u64 v[34:35], v[32:33], 0, v[50:51]
	v_lshl_add_u64 v[32:33], v[32:33], 0, s[36:37]
	global_load_ushort v86, v[34:35], off
	v_lshl_add_u64 v[34:35], v[32:33], 0, v[44:45]
	global_load_ushort v87, v[34:35], off
	v_lshl_add_u64 v[34:35], v[34:35], 0, v[66:67]
	global_load_ushort v58, v[34:35], off offset:2048
	v_lshl_add_u64 v[34:35], v[32:33], 0, v[50:51]
	v_lshl_add_u64 v[32:33], v[32:33], 0, s[36:37]
	global_load_ushort v89, v[34:35], off
	v_lshl_add_u64 v[34:35], v[32:33], 0, v[44:45]
	global_load_ushort v93, v[34:35], off
	v_lshl_add_u64 v[34:35], v[34:35], 0, v[66:67]
	global_load_ushort v55, v[34:35], off offset:2048
	v_lshl_add_u64 v[34:35], v[32:33], 0, v[50:51]
	v_lshl_add_u64 v[32:33], v[32:33], 0, s[36:37]
	global_load_ushort v94, v[34:35], off
	v_lshl_add_u64 v[34:35], v[32:33], 0, v[44:45]
	global_load_ushort v95, v[34:35], off
	v_lshl_add_u64 v[34:35], v[34:35], 0, v[66:67]
	global_load_ushort v64, v[34:35], off offset:2048
	v_lshl_add_u64 v[34:35], v[32:33], 0, v[50:51]
	v_lshl_add_u64 v[32:33], v[32:33], 0, s[36:37]
	global_load_ushort v97, v[34:35], off
	v_lshl_add_u64 v[34:35], v[32:33], 0, v[44:45]
	global_load_ushort v103, v[34:35], off
	v_lshl_add_u64 v[34:35], v[34:35], 0, v[66:67]
	global_load_ushort v57, v[34:35], off offset:2048
	v_lshl_add_u64 v[34:35], v[32:33], 0, v[50:51]
	v_lshl_add_u64 v[32:33], v[32:33], 0, s[36:37]
	global_load_ushort v105, v[34:35], off
	v_lshl_add_u64 v[34:35], v[32:33], 0, v[44:45]
	global_load_ushort v106, v[34:35], off
	v_lshl_add_u64 v[34:35], v[34:35], 0, v[66:67]
	global_load_ushort v68, v[34:35], off offset:2048
	v_lshl_add_u64 v[34:35], v[32:33], 0, v[50:51]
	v_lshl_add_u64 v[32:33], v[32:33], 0, s[36:37]
	global_load_ushort v107, v[34:35], off
	v_lshl_add_u64 v[34:35], v[32:33], 0, v[44:45]
	global_load_ushort v108, v[34:35], off
	v_lshl_add_u64 v[34:35], v[34:35], 0, v[66:67]
	global_load_ushort v59, v[34:35], off offset:2048
	v_lshl_add_u64 v[34:35], v[32:33], 0, v[50:51]
	v_lshl_add_u64 v[32:33], v[32:33], 0, s[36:37]
	global_load_ushort v109, v[34:35], off
	v_lshl_add_u64 v[34:35], v[32:33], 0, v[44:45]
	global_load_ushort v110, v[34:35], off
	v_lshl_add_u64 v[34:35], v[34:35], 0, v[66:67]
	global_load_ushort v70, v[34:35], off offset:2048
	v_lshl_add_u64 v[34:35], v[32:33], 0, v[50:51]
	v_lshl_add_u64 v[32:33], v[32:33], 0, s[36:37]
	global_load_ushort v111, v[34:35], off
	v_lshl_add_u64 v[34:35], v[32:33], 0, v[44:45]
	global_load_ushort v112, v[34:35], off
	v_lshl_add_u64 v[34:35], v[34:35], 0, v[66:67]
	global_load_ushort v65, v[34:35], off offset:2048
	v_lshl_add_u64 v[34:35], v[32:33], 0, v[50:51]
	v_lshl_add_u64 v[32:33], v[32:33], 0, s[36:37]
	global_load_ushort v113, v[34:35], off
	v_lshl_add_u64 v[34:35], v[32:33], 0, v[44:45]
	global_load_ushort v114, v[34:35], off
	v_lshl_add_u64 v[34:35], v[34:35], 0, v[66:67]
	global_load_ushort v72, v[34:35], off offset:2048
	v_lshl_add_u64 v[34:35], v[32:33], 0, v[50:51]
	v_lshl_add_u64 v[32:33], v[32:33], 0, s[36:37]
	global_load_ushort v115, v[34:35], off
	v_lshl_add_u64 v[34:35], v[32:33], 0, v[44:45]
	v_lshl_add_u64 v[32:33], v[32:33], 0, v[50:51]
	global_load_ushort v116, v[34:35], off
	global_load_ushort v51, v[32:33], off
	v_lshl_add_u64 v[34:35], v[34:35], 0, v[66:67]
	global_load_ushort v67, v[34:35], off offset:2048
	s_cmp_eq_u32 s101, 1
	s_cbranch_scc1 .Lhp_bar
.LBB0_1018:
	s_lshl_b32 s52, s49, 6
	s_sub_i32 s53, s46, s52
	s_and_b64 s[50:51], vcc, exec
	s_cselect_b32 s52, s52, s53
	v_add_u32_e32 v117, s52, v101
	v_add_u32_e32 v184, 0x11800, v98
	ds_read_b64 v[132:133], v102 offset:0
	ds_read_b64 v[134:135], v102 offset:32
	ds_read_b64 v[136:137], v102 offset:64
	ds_read_b64 v[138:139], v102 offset:96
	ds_read_b64 v[140:141], v102 offset:128
	ds_read_b64 v[142:143], v102 offset:160
	ds_read_b64 v[144:145], v102 offset:192
	ds_read_b64 v[146:147], v102 offset:224
	ds_read_b128 v[190:193], v184 offset:0
	ds_read_b128 v[194:197], v184 offset:64
	ds_read_b128 v[198:201], v184 offset:128
	ds_read_b128 v[202:205], v184 offset:192
	ds_read_b128 v[206:209], v184 offset:256
	ds_read_b128 v[210:213], v184 offset:320
	ds_read_b128 v[214:217], v184 offset:384
	v_mad_i64_i32 v[168:169], s[50:51], v117, s39, v[62:63]
	v_cvt_pk_bf16_f32 v36, v4, v5
	v_cvt_pk_bf16_f32 v37, v6, v7
	v_cvt_pk_bf16_f32 v38, v0, v1
	v_cvt_pk_bf16_f32 v39, v2, v3
	v_cvt_pk_bf16_f32 v40, v12, v13
	v_cvt_pk_bf16_f32 v41, v14, v15
	v_cvt_pk_bf16_f32 v42, v8, v9
	v_cvt_pk_bf16_f32 v43, v10, v11
	v_cvt_pk_bf16_f32 v124, v20, v21
	v_cvt_pk_bf16_f32 v125, v22, v23
	v_cvt_pk_bf16_f32 v126, v16, v17
	v_cvt_pk_bf16_f32 v127, v18, v19
	v_cvt_pk_bf16_f32 v128, v28, v29
	v_cvt_pk_bf16_f32 v129, v30, v31
	v_cvt_pk_bf16_f32 v130, v24, v25
	v_cvt_pk_bf16_f32 v131, v26, v27
	v_lshl_add_u64 v[170:171], s[34:35], 1, v[168:169]
	v_lshl_add_u64 v[172:173], v[170:171], 0, s[36:37]
	s_waitcnt lgkmcnt(7)
	v_mfma_f32_16x16x32_bf16 v[32:35], v[132:135], v[36:39], 0
	v_mfma_f32_16x16x32_bf16 v[32:35], v[136:139], v[40:43], v[32:35]
	v_mfma_f32_16x16x32_bf16 v[32:35], v[140:143], v[124:127], v[32:35]
	v_mfma_f32_16x16x32_bf16 v[32:35], v[144:147], v[128:131], v[32:35]
	ds_read_b128 v[218:221], v184 offset:448
	v_lshl_add_u64 v[174:175], v[172:173], 0, s[36:37]
	v_add_u32_e32 v117, s47, v117
	s_waitcnt lgkmcnt(0)
	ds_read_b64 v[150:151], v100 offset:0
	ds_read_b64 v[152:153], v99 offset:0
	ds_read_b64 v[154:155], v99 offset:2304
	ds_read_b64 v[156:157], v99 offset:4608
	ds_read_b64 v[158:159], v99 offset:6912
	ds_read_b64 v[160:161], v99 offset:9216
	ds_read_b64 v[162:163], v99 offset:11520
	ds_read_b64 v[164:165], v99 offset:13824
	ds_read_b64 v[166:167], v99 offset:16128
	ds_read_b128 v[222:225], v104 offset:17408
	ds_read_b128 v[240:243], v104 offset:0
	ds_read_b128 v[228:231], v104 offset:17472
	ds_read_b128 v[244:247], v104 offset:64
	ds_read_b128 v[232:235], v104 offset:17536
	ds_read_b128 v[248:251], v104 offset:128
	v_pk_mul_f32 v[4:5], v[4:5], v[190:191]
	v_pk_mul_f32 v[6:7], v[6:7], v[192:193]
	v_pk_mul_f32 v[0:1], v[0:1], v[194:195]
	v_pk_mul_f32 v[2:3], v[2:3], v[196:197]
	v_pk_mul_f32 v[12:13], v[12:13], v[198:199]
	v_pk_mul_f32 v[14:15], v[14:15], v[200:201]
	v_pk_mul_f32 v[8:9], v[8:9], v[202:203]
	v_pk_mul_f32 v[10:11], v[10:11], v[204:205]
	v_pk_mul_f32 v[20:21], v[20:21], v[206:207]
	v_pk_mul_f32 v[22:23], v[22:23], v[208:209]
	v_pk_mul_f32 v[16:17], v[16:17], v[210:211]
	v_pk_mul_f32 v[18:19], v[18:19], v[212:213]
	v_pk_mul_f32 v[28:29], v[28:29], v[214:215]
	v_pk_mul_f32 v[30:31], v[30:31], v[216:217]
	v_pk_mul_f32 v[24:25], v[24:25], v[218:219]
	v_pk_mul_f32 v[26:27], v[26:27], v[220:221]
	s_waitcnt lgkmcnt(6)
	s_nop 1
	v_mfma_f32_16x16x16_bf16 v[4:7], v[152:153], v[150:151], v[4:7]
	v_mfma_f32_16x16x16_bf16 v[0:3], v[154:155], v[150:151], v[0:3]
	v_mfma_f32_16x16x16_bf16 v[12:15], v[156:157], v[150:151], v[12:15]
	v_mfma_f32_16x16x16_bf16 v[8:11], v[158:159], v[150:151], v[8:11]
	v_mfma_f32_16x16x16_bf16 v[20:23], v[160:161], v[150:151], v[20:23]
	v_mfma_f32_16x16x16_bf16 v[16:19], v[162:163], v[150:151], v[16:19]
	v_mfma_f32_16x16x16_bf16 v[28:31], v[164:165], v[150:151], v[28:31]
	v_mfma_f32_16x16x16_bf16 v[24:27], v[166:167], v[150:151], v[24:27]
	ds_read_b128 v[236:239], v104 offset:17600
	ds_read_b128 v[252:255], v104 offset:192
	s_waitcnt lgkmcnt(0)
	v_mfma_f32_16x16x32_bf16 v[176:179], v[222:225], v[240:243], 0
	v_mfma_f32_16x16x32_bf16 v[176:179], v[228:231], v[244:247], v[176:179]
	v_mfma_f32_16x16x32_bf16 v[176:179], v[232:235], v[248:251], v[176:179]
	v_mfma_f32_16x16x32_bf16 v[176:179], v[236:239], v[252:255], v[176:179]
	ds_read_b64 v[132:133], v102 offset:4352
	ds_read_b64 v[134:135], v102 offset:4384
	ds_read_b64 v[136:137], v102 offset:4416
	ds_read_b64 v[138:139], v102 offset:4448
	ds_read_b64 v[140:141], v102 offset:4480
	ds_read_b64 v[142:143], v102 offset:4512
	ds_read_b64 v[144:145], v102 offset:4544
	ds_read_b64 v[146:147], v102 offset:4576
	ds_read_b128 v[190:193], v184 offset:512
	ds_read_b128 v[194:197], v184 offset:576
	ds_read_b128 v[198:201], v184 offset:640
	ds_read_b128 v[202:205], v184 offset:704
	ds_read_b128 v[206:209], v184 offset:768
	ds_read_b128 v[210:213], v184 offset:832
	ds_read_b128 v[214:217], v184 offset:896
	s_nop 1
	v_cndmask_b32_e64 v176, v176, 0, s[4:5]
	v_cndmask_b32_e64 v177, 0, v177, s[6:7]
	v_cndmask_b32_e64 v178, v178, 0, s[8:9]
	v_cndmask_b32_e64 v179, v179, 0, s[10:11]
	v_cvt_pk_bf16_f32 v180, v176, v177
	v_cvt_pk_bf16_f32 v181, v178, v179
	s_nop 1
	v_mfma_f32_16x16x16_bf16 v[32:35], v[180:181], v[150:151], v[32:35]
	s_nop 7
	s_nop 1
	v_cvt_pk_bf16_f32 v32, v32, s0
	v_cvt_pk_bf16_f32 v33, v33, s0
	v_cvt_pk_bf16_f32 v34, v34, s0
	v_cvt_pk_bf16_f32 v35, v35, s0
	global_store_short v[168:169], v32, off offset:2048
	global_store_short v[170:171], v33, off offset:2048
	global_store_short v[172:173], v34, off offset:2048
	global_store_short v[174:175], v35, off offset:2048
	v_mad_i64_i32 v[168:169], s[50:51], v117, s39, v[62:63]
	v_cvt_pk_bf16_f32 v36, v4, v5
	v_cvt_pk_bf16_f32 v37, v6, v7
	v_cvt_pk_bf16_f32 v38, v0, v1
	v_cvt_pk_bf16_f32 v39, v2, v3
	v_cvt_pk_bf16_f32 v40, v12, v13
	v_cvt_pk_bf16_f32 v41, v14, v15
	v_cvt_pk_bf16_f32 v42, v8, v9
	v_cvt_pk_bf16_f32 v43, v10, v11
	v_cvt_pk_bf16_f32 v124, v20, v21
	v_cvt_pk_bf16_f32 v125, v22, v23
	v_cvt_pk_bf16_f32 v126, v16, v17
	v_cvt_pk_bf16_f32 v127, v18, v19
	v_cvt_pk_bf16_f32 v128, v28, v29
	v_cvt_pk_bf16_f32 v129, v30, v31
	v_cvt_pk_bf16_f32 v130, v24, v25
	v_cvt_pk_bf16_f32 v131, v26, v27
	v_lshl_add_u64 v[170:171], s[34:35], 1, v[168:169]
	v_lshl_add_u64 v[172:173], v[170:171], 0, s[36:37]
	s_waitcnt lgkmcnt(7)
	v_mfma_f32_16x16x32_bf16 v[32:35], v[132:135], v[36:39], 0
	v_mfma_f32_16x16x32_bf16 v[32:35], v[136:139], v[40:43], v[32:35]
	v_mfma_f32_16x16x32_bf16 v[32:35], v[140:143], v[124:127], v[32:35]
	v_mfma_f32_16x16x32_bf16 v[32:35], v[144:147], v[128:131], v[32:35]
	ds_read_b128 v[218:221], v184 offset:960
	v_lshl_add_u64 v[174:175], v[172:173], 0, s[36:37]
	v_add_u32_e32 v117, s47, v117
	s_waitcnt lgkmcnt(0)
	ds_read_b64 v[150:151], v100 offset:32
	ds_read_b64 v[152:153], v99 offset:32
	ds_read_b64 v[154:155], v99 offset:2336
	ds_read_b64 v[156:157], v99 offset:4640
	ds_read_b64 v[158:159], v99 offset:6944
	ds_read_b64 v[160:161], v99 offset:9248
	ds_read_b64 v[162:163], v99 offset:11552
	ds_read_b64 v[164:165], v99 offset:13856
	ds_read_b64 v[166:167], v99 offset:16160
	ds_read_b128 v[222:225], v104 offset:21760
	ds_read_b128 v[240:243], v104 offset:4352
	ds_read_b128 v[228:231], v104 offset:21824
	ds_read_b128 v[244:247], v104 offset:4416
	ds_read_b128 v[232:235], v104 offset:21888
	ds_read_b128 v[248:251], v104 offset:4480
	v_pk_mul_f32 v[4:5], v[4:5], v[190:191]
	v_pk_mul_f32 v[6:7], v[6:7], v[192:193]
	v_pk_mul_f32 v[0:1], v[0:1], v[194:195]
	v_pk_mul_f32 v[2:3], v[2:3], v[196:197]
	v_pk_mul_f32 v[12:13], v[12:13], v[198:199]
	v_pk_mul_f32 v[14:15], v[14:15], v[200:201]
	v_pk_mul_f32 v[8:9], v[8:9], v[202:203]
	v_pk_mul_f32 v[10:11], v[10:11], v[204:205]
	v_pk_mul_f32 v[20:21], v[20:21], v[206:207]
	v_pk_mul_f32 v[22:23], v[22:23], v[208:209]
	v_pk_mul_f32 v[16:17], v[16:17], v[210:211]
	v_pk_mul_f32 v[18:19], v[18:19], v[212:213]
	v_pk_mul_f32 v[28:29], v[28:29], v[214:215]
	v_pk_mul_f32 v[30:31], v[30:31], v[216:217]
	v_pk_mul_f32 v[24:25], v[24:25], v[218:219]
	v_pk_mul_f32 v[26:27], v[26:27], v[220:221]
	s_waitcnt lgkmcnt(6)
	s_nop 1
	v_mfma_f32_16x16x16_bf16 v[4:7], v[152:153], v[150:151], v[4:7]
	v_mfma_f32_16x16x16_bf16 v[0:3], v[154:155], v[150:151], v[0:3]
	v_mfma_f32_16x16x16_bf16 v[12:15], v[156:157], v[150:151], v[12:15]
	v_mfma_f32_16x16x16_bf16 v[8:11], v[158:159], v[150:151], v[8:11]
	v_mfma_f32_16x16x16_bf16 v[20:23], v[160:161], v[150:151], v[20:23]
	v_mfma_f32_16x16x16_bf16 v[16:19], v[162:163], v[150:151], v[16:19]
	v_mfma_f32_16x16x16_bf16 v[28:31], v[164:165], v[150:151], v[28:31]
	v_mfma_f32_16x16x16_bf16 v[24:27], v[166:167], v[150:151], v[24:27]
	ds_read_b128 v[236:239], v104 offset:21952
	ds_read_b128 v[252:255], v104 offset:4544
	s_waitcnt lgkmcnt(0)
	v_mfma_f32_16x16x32_bf16 v[176:179], v[222:225], v[240:243], 0
	v_mfma_f32_16x16x32_bf16 v[176:179], v[228:231], v[244:247], v[176:179]
	v_mfma_f32_16x16x32_bf16 v[176:179], v[232:235], v[248:251], v[176:179]
	v_mfma_f32_16x16x32_bf16 v[176:179], v[236:239], v[252:255], v[176:179]
	ds_read_b64 v[132:133], v102 offset:8704
	ds_read_b64 v[134:135], v102 offset:8736
	ds_read_b64 v[136:137], v102 offset:8768
	ds_read_b64 v[138:139], v102 offset:8800
	ds_read_b64 v[140:141], v102 offset:8832
	ds_read_b64 v[142:143], v102 offset:8864
	ds_read_b64 v[144:145], v102 offset:8896
	ds_read_b64 v[146:147], v102 offset:8928
	ds_read_b128 v[190:193], v184 offset:1024
	ds_read_b128 v[194:197], v184 offset:1088
	ds_read_b128 v[198:201], v184 offset:1152
	ds_read_b128 v[202:205], v184 offset:1216
	ds_read_b128 v[206:209], v184 offset:1280
	ds_read_b128 v[210:213], v184 offset:1344
	ds_read_b128 v[214:217], v184 offset:1408
	s_nop 1
	v_cndmask_b32_e64 v176, v176, 0, s[4:5]
	v_cndmask_b32_e64 v177, 0, v177, s[6:7]
	v_cndmask_b32_e64 v178, v178, 0, s[8:9]
	v_cndmask_b32_e64 v179, v179, 0, s[10:11]
	v_cvt_pk_bf16_f32 v180, v176, v177
	v_cvt_pk_bf16_f32 v181, v178, v179
	s_nop 1
	v_mfma_f32_16x16x16_bf16 v[32:35], v[180:181], v[150:151], v[32:35]
	s_nop 7
	s_nop 1
	v_cvt_pk_bf16_f32 v32, v32, s0
	v_cvt_pk_bf16_f32 v33, v33, s0
	v_cvt_pk_bf16_f32 v34, v34, s0
	v_cvt_pk_bf16_f32 v35, v35, s0
	global_store_short v[168:169], v32, off offset:2048
	global_store_short v[170:171], v33, off offset:2048
	global_store_short v[172:173], v34, off offset:2048
	global_store_short v[174:175], v35, off offset:2048
	v_mad_i64_i32 v[168:169], s[50:51], v117, s39, v[62:63]
	v_cvt_pk_bf16_f32 v36, v4, v5
	v_cvt_pk_bf16_f32 v37, v6, v7
	v_cvt_pk_bf16_f32 v38, v0, v1
	v_cvt_pk_bf16_f32 v39, v2, v3
	v_cvt_pk_bf16_f32 v40, v12, v13
	v_cvt_pk_bf16_f32 v41, v14, v15
	v_cvt_pk_bf16_f32 v42, v8, v9
	v_cvt_pk_bf16_f32 v43, v10, v11
	v_cvt_pk_bf16_f32 v124, v20, v21
	v_cvt_pk_bf16_f32 v125, v22, v23
	v_cvt_pk_bf16_f32 v126, v16, v17
	v_cvt_pk_bf16_f32 v127, v18, v19
	v_cvt_pk_bf16_f32 v128, v28, v29
	v_cvt_pk_bf16_f32 v129, v30, v31
	v_cvt_pk_bf16_f32 v130, v24, v25
	v_cvt_pk_bf16_f32 v131, v26, v27
	v_lshl_add_u64 v[170:171], s[34:35], 1, v[168:169]
	v_lshl_add_u64 v[172:173], v[170:171], 0, s[36:37]
	s_waitcnt lgkmcnt(7)
	v_mfma_f32_16x16x32_bf16 v[32:35], v[132:135], v[36:39], 0
	v_mfma_f32_16x16x32_bf16 v[32:35], v[136:139], v[40:43], v[32:35]
	v_mfma_f32_16x16x32_bf16 v[32:35], v[140:143], v[124:127], v[32:35]
	v_mfma_f32_16x16x32_bf16 v[32:35], v[144:147], v[128:131], v[32:35]
	ds_read_b128 v[218:221], v184 offset:1472
	v_lshl_add_u64 v[174:175], v[172:173], 0, s[36:37]
	v_add_u32_e32 v117, s47, v117
	s_waitcnt lgkmcnt(0)
	ds_read_b64 v[150:151], v100 offset:64
	ds_read_b64 v[152:153], v99 offset:64
	ds_read_b64 v[154:155], v99 offset:2368
	ds_read_b64 v[156:157], v99 offset:4672
	ds_read_b64 v[158:159], v99 offset:6976
	ds_read_b64 v[160:161], v99 offset:9280
	ds_read_b64 v[162:163], v99 offset:11584
	ds_read_b64 v[164:165], v99 offset:13888
	ds_read_b64 v[166:167], v99 offset:16192
	ds_read_b128 v[222:225], v104 offset:26112
	ds_read_b128 v[240:243], v104 offset:8704
	ds_read_b128 v[228:231], v104 offset:26176
	ds_read_b128 v[244:247], v104 offset:8768
	ds_read_b128 v[232:235], v104 offset:26240
	ds_read_b128 v[248:251], v104 offset:8832
	v_pk_mul_f32 v[4:5], v[4:5], v[190:191]
	v_pk_mul_f32 v[6:7], v[6:7], v[192:193]
	v_pk_mul_f32 v[0:1], v[0:1], v[194:195]
	v_pk_mul_f32 v[2:3], v[2:3], v[196:197]
	v_pk_mul_f32 v[12:13], v[12:13], v[198:199]
	v_pk_mul_f32 v[14:15], v[14:15], v[200:201]
	v_pk_mul_f32 v[8:9], v[8:9], v[202:203]
	v_pk_mul_f32 v[10:11], v[10:11], v[204:205]
	v_pk_mul_f32 v[20:21], v[20:21], v[206:207]
	v_pk_mul_f32 v[22:23], v[22:23], v[208:209]
	v_pk_mul_f32 v[16:17], v[16:17], v[210:211]
	v_pk_mul_f32 v[18:19], v[18:19], v[212:213]
	v_pk_mul_f32 v[28:29], v[28:29], v[214:215]
	v_pk_mul_f32 v[30:31], v[30:31], v[216:217]
	v_pk_mul_f32 v[24:25], v[24:25], v[218:219]
	v_pk_mul_f32 v[26:27], v[26:27], v[220:221]
	s_waitcnt lgkmcnt(6)
	s_nop 1
	v_mfma_f32_16x16x16_bf16 v[4:7], v[152:153], v[150:151], v[4:7]
	v_mfma_f32_16x16x16_bf16 v[0:3], v[154:155], v[150:151], v[0:3]
	v_mfma_f32_16x16x16_bf16 v[12:15], v[156:157], v[150:151], v[12:15]
	v_mfma_f32_16x16x16_bf16 v[8:11], v[158:159], v[150:151], v[8:11]
	v_mfma_f32_16x16x16_bf16 v[20:23], v[160:161], v[150:151], v[20:23]
	v_mfma_f32_16x16x16_bf16 v[16:19], v[162:163], v[150:151], v[16:19]
	v_mfma_f32_16x16x16_bf16 v[28:31], v[164:165], v[150:151], v[28:31]
	v_mfma_f32_16x16x16_bf16 v[24:27], v[166:167], v[150:151], v[24:27]
	ds_read_b128 v[236:239], v104 offset:26304
	ds_read_b128 v[252:255], v104 offset:8896
	s_waitcnt lgkmcnt(0)
	v_mfma_f32_16x16x32_bf16 v[176:179], v[222:225], v[240:243], 0
	v_mfma_f32_16x16x32_bf16 v[176:179], v[228:231], v[244:247], v[176:179]
	v_mfma_f32_16x16x32_bf16 v[176:179], v[232:235], v[248:251], v[176:179]
	v_mfma_f32_16x16x32_bf16 v[176:179], v[236:239], v[252:255], v[176:179]
	ds_read_b64 v[132:133], v102 offset:13056
	ds_read_b64 v[134:135], v102 offset:13088
	ds_read_b64 v[136:137], v102 offset:13120
	ds_read_b64 v[138:139], v102 offset:13152
	ds_read_b64 v[140:141], v102 offset:13184
	ds_read_b64 v[142:143], v102 offset:13216
	ds_read_b64 v[144:145], v102 offset:13248
	ds_read_b64 v[146:147], v102 offset:13280
	ds_read_b128 v[190:193], v184 offset:1536
	ds_read_b128 v[194:197], v184 offset:1600
	ds_read_b128 v[198:201], v184 offset:1664
	ds_read_b128 v[202:205], v184 offset:1728
	ds_read_b128 v[206:209], v184 offset:1792
	ds_read_b128 v[210:213], v184 offset:1856
	ds_read_b128 v[214:217], v184 offset:1920
	s_nop 1
	v_cndmask_b32_e64 v176, v176, 0, s[4:5]
	v_cndmask_b32_e64 v177, 0, v177, s[6:7]
	v_cndmask_b32_e64 v178, v178, 0, s[8:9]
	v_cndmask_b32_e64 v179, v179, 0, s[10:11]
	v_cvt_pk_bf16_f32 v180, v176, v177
	v_cvt_pk_bf16_f32 v181, v178, v179
	s_nop 1
	v_mfma_f32_16x16x16_bf16 v[32:35], v[180:181], v[150:151], v[32:35]
	s_nop 7
	s_nop 1
	v_cvt_pk_bf16_f32 v32, v32, s0
	v_cvt_pk_bf16_f32 v33, v33, s0
	v_cvt_pk_bf16_f32 v34, v34, s0
	v_cvt_pk_bf16_f32 v35, v35, s0
	global_store_short v[168:169], v32, off offset:2048
	global_store_short v[170:171], v33, off offset:2048
	global_store_short v[172:173], v34, off offset:2048
	global_store_short v[174:175], v35, off offset:2048
	v_mad_i64_i32 v[168:169], s[50:51], v117, s39, v[62:63]
	v_cvt_pk_bf16_f32 v36, v4, v5
	v_cvt_pk_bf16_f32 v37, v6, v7
	v_cvt_pk_bf16_f32 v38, v0, v1
	v_cvt_pk_bf16_f32 v39, v2, v3
	v_cvt_pk_bf16_f32 v40, v12, v13
	v_cvt_pk_bf16_f32 v41, v14, v15
	v_cvt_pk_bf16_f32 v42, v8, v9
	v_cvt_pk_bf16_f32 v43, v10, v11
	v_cvt_pk_bf16_f32 v124, v20, v21
	v_cvt_pk_bf16_f32 v125, v22, v23
	v_cvt_pk_bf16_f32 v126, v16, v17
	v_cvt_pk_bf16_f32 v127, v18, v19
	v_cvt_pk_bf16_f32 v128, v28, v29
	v_cvt_pk_bf16_f32 v129, v30, v31
	v_cvt_pk_bf16_f32 v130, v24, v25
	v_cvt_pk_bf16_f32 v131, v26, v27
	v_lshl_add_u64 v[170:171], s[34:35], 1, v[168:169]
	v_lshl_add_u64 v[172:173], v[170:171], 0, s[36:37]
	s_waitcnt lgkmcnt(7)
	v_mfma_f32_16x16x32_bf16 v[32:35], v[132:135], v[36:39], 0
	v_mfma_f32_16x16x32_bf16 v[32:35], v[136:139], v[40:43], v[32:35]
	v_mfma_f32_16x16x32_bf16 v[32:35], v[140:143], v[124:127], v[32:35]
	v_mfma_f32_16x16x32_bf16 v[32:35], v[144:147], v[128:131], v[32:35]
	ds_read_b128 v[218:221], v184 offset:1984
	v_lshl_add_u64 v[174:175], v[172:173], 0, s[36:37]
	v_add_u32_e32 v117, s47, v117
	s_waitcnt lgkmcnt(0)
	ds_read_b64 v[150:151], v100 offset:96
	ds_read_b64 v[152:153], v99 offset:96
	ds_read_b64 v[154:155], v99 offset:2400
	ds_read_b64 v[156:157], v99 offset:4704
	ds_read_b64 v[158:159], v99 offset:7008
	ds_read_b64 v[160:161], v99 offset:9312
	ds_read_b64 v[162:163], v99 offset:11616
	ds_read_b64 v[164:165], v99 offset:13920
	ds_read_b64 v[166:167], v99 offset:16224
	ds_read_b128 v[222:225], v104 offset:30464
	ds_read_b128 v[240:243], v104 offset:13056
	ds_read_b128 v[228:231], v104 offset:30528
	ds_read_b128 v[244:247], v104 offset:13120
	ds_read_b128 v[232:235], v104 offset:30592
	ds_read_b128 v[248:251], v104 offset:13184
	v_pk_mul_f32 v[4:5], v[4:5], v[190:191]
	v_pk_mul_f32 v[6:7], v[6:7], v[192:193]
	v_pk_mul_f32 v[0:1], v[0:1], v[194:195]
	v_pk_mul_f32 v[2:3], v[2:3], v[196:197]
	v_pk_mul_f32 v[12:13], v[12:13], v[198:199]
	v_pk_mul_f32 v[14:15], v[14:15], v[200:201]
	v_pk_mul_f32 v[8:9], v[8:9], v[202:203]
	v_pk_mul_f32 v[10:11], v[10:11], v[204:205]
	v_pk_mul_f32 v[20:21], v[20:21], v[206:207]
	v_pk_mul_f32 v[22:23], v[22:23], v[208:209]
	v_pk_mul_f32 v[16:17], v[16:17], v[210:211]
	v_pk_mul_f32 v[18:19], v[18:19], v[212:213]
	v_pk_mul_f32 v[28:29], v[28:29], v[214:215]
	v_pk_mul_f32 v[30:31], v[30:31], v[216:217]
	v_pk_mul_f32 v[24:25], v[24:25], v[218:219]
	v_pk_mul_f32 v[26:27], v[26:27], v[220:221]
	s_waitcnt lgkmcnt(6)
	s_nop 1
	v_mfma_f32_16x16x16_bf16 v[4:7], v[152:153], v[150:151], v[4:7]
	v_mfma_f32_16x16x16_bf16 v[0:3], v[154:155], v[150:151], v[0:3]
	v_mfma_f32_16x16x16_bf16 v[12:15], v[156:157], v[150:151], v[12:15]
	v_mfma_f32_16x16x16_bf16 v[8:11], v[158:159], v[150:151], v[8:11]
	v_mfma_f32_16x16x16_bf16 v[20:23], v[160:161], v[150:151], v[20:23]
	v_mfma_f32_16x16x16_bf16 v[16:19], v[162:163], v[150:151], v[16:19]
	v_mfma_f32_16x16x16_bf16 v[28:31], v[164:165], v[150:151], v[28:31]
	v_mfma_f32_16x16x16_bf16 v[24:27], v[166:167], v[150:151], v[24:27]
	ds_read_b128 v[236:239], v104 offset:30656
	ds_read_b128 v[252:255], v104 offset:13248
	s_waitcnt lgkmcnt(0)
	v_mfma_f32_16x16x32_bf16 v[176:179], v[222:225], v[240:243], 0
	v_mfma_f32_16x16x32_bf16 v[176:179], v[228:231], v[244:247], v[176:179]
	v_mfma_f32_16x16x32_bf16 v[176:179], v[232:235], v[248:251], v[176:179]
	v_mfma_f32_16x16x32_bf16 v[176:179], v[236:239], v[252:255], v[176:179]
	s_nop 7
	s_nop 1
	v_cndmask_b32_e64 v176, v176, 0, s[4:5]
	v_cndmask_b32_e64 v177, 0, v177, s[6:7]
	v_cndmask_b32_e64 v178, v178, 0, s[8:9]
	v_cndmask_b32_e64 v179, v179, 0, s[10:11]
	v_cvt_pk_bf16_f32 v180, v176, v177
	v_cvt_pk_bf16_f32 v181, v178, v179
	s_nop 1
	v_mfma_f32_16x16x16_bf16 v[32:35], v[180:181], v[150:151], v[32:35]
	s_nop 7
	s_nop 1
	v_cvt_pk_bf16_f32 v32, v32, s0
	v_cvt_pk_bf16_f32 v33, v33, s0
	v_cvt_pk_bf16_f32 v34, v34, s0
	v_cvt_pk_bf16_f32 v35, v35, s0
	global_store_short v[168:169], v32, off offset:2048
	global_store_short v[170:171], v33, off offset:2048
	global_store_short v[172:173], v34, off offset:2048
	global_store_short v[174:175], v35, off offset:2048
	s_cmp_lg_u32 s98, 0
	s_cbranch_scc1 .Lhp_end
	s_add_i32 s48, s49, 1
	s_cmp_ge_u32 s48, s45
	s_cbranch_scc1 .Lhp_end
	s_branch .LBB0_1016
.Lhp_end:
	s_waitcnt lgkmcnt(0)
	v_subrev_u32_e32 v96, s99, v96
	v_subrev_u32_e32 v91, s99, v91
	v_subrev_u32_e32 v92, s99, v92
	v_add_u32_e32 v102, s99, v102
	v_add_u32_e32 v104, s99, v104
	v_add_u32_e32 v99, s99, v99
	v_add_u32_e32 v100, s99, v100
	v_add_u32_e32 v98, s99, v98
	s_sub_i32 s99, 0, s99
	s_add_i32 s49, s49, 1
	s_cmp_eq_u32 s49, s45
	s_cbranch_scc1 .Lhp_exit
.Lhp_bar:
	s_waitcnt lgkmcnt(0)
	s_barrier
	s_cmp_eq_u32 s98, 0
	s_cbranch_scc1 .Lhp_ytop
	s_add_i32 s48, s49, 1
	s_cmp_ge_u32 s48, s45
	s_cbranch_scc1 .LBB0_1018
	s_branch .LBB0_1016
.Lhp_ytop:
	s_add_i32 s48, s49, 1
	s_cmp_ge_u32 s48, s45
	s_cbranch_scc1 .LBB0_1018
	s_mov_b32 s101, 0
	s_branch .Lhp_issue
.Lhp_exit:
	s_and_b64 vcc, exec, s[18:19]
	s_cbranch_vccz .LBB0_1007
	s_load_dwordx2 s[4:5], s[12:13], 0xa8
	s_waitcnt vmcnt(41)
	v_mov_b32_e32 v49, v45
	v_lshlrev_b64 v[34:35], 19, v[48:49]
	v_mov_b32_e32 v47, v45
	v_lshl_add_u32 v32, v73, 9, v71
	s_waitcnt lgkmcnt(0)
	v_lshl_add_u64 v[34:35], s[4:5], 0, v[34:35]
	v_lshl_add_u64 v[34:35], v[34:35], 0, v[46:47]
	v_lshl_add_u64 v[34:35], v[34:35], 0, s[16:17]
	v_ashrrev_i32_e32 v33, 31, v32
	v_lshl_add_u64 v[36:37], v[32:33], 2, v[34:35]
	global_store_dword v[36:37], v4, off
	global_store_dword v[36:37], v5, off offset:512
	v_lshl_add_u32 v4, v90, 7, v71
	v_ashrrev_i32_e32 v5, 31, v4
	v_lshl_add_u64 v[4:5], v[4:5], 2, v[34:35]
	global_store_dword v[4:5], v6, off
	v_lshl_add_u32 v4, v88, 7, v71
	v_ashrrev_i32_e32 v5, 31, v4
	v_lshl_add_u64 v[4:5], v[4:5], 2, v[34:35]
	global_store_dword v[4:5], v7, off
	v_add_u32_e32 v4, 0x800, v32
	v_ashrrev_i32_e32 v5, 31, v4
	v_lshl_add_u64 v[4:5], v[4:5], 2, v[34:35]
	global_store_dword v[4:5], v0, off
	v_add_u32_e32 v4, 0x880, v32
	v_ashrrev_i32_e32 v5, 31, v4
	v_lshl_add_u64 v[4:5], v[4:5], 2, v[34:35]
	v_add_u32_e32 v0, 0x900, v32
	global_store_dword v[4:5], v1, off
	v_ashrrev_i32_e32 v1, 31, v0
	v_lshl_add_u64 v[0:1], v[0:1], 2, v[34:35]
	global_store_dword v[0:1], v2, off
	v_add_u32_e32 v0, 0x980, v32
	v_ashrrev_i32_e32 v1, 31, v0
	v_lshl_add_u64 v[0:1], v[0:1], 2, v[34:35]
	global_store_dword v[0:1], v3, off
	v_add_u32_e32 v0, 0x1000, v32
	v_ashrrev_i32_e32 v1, 31, v0
	v_lshl_add_u64 v[0:1], v[0:1], 2, v[34:35]
	global_store_dword v[0:1], v12, off
	v_add_u32_e32 v0, 0x1080, v32
	v_ashrrev_i32_e32 v1, 31, v0
	v_lshl_add_u64 v[0:1], v[0:1], 2, v[34:35]
	global_store_dword v[0:1], v13, off
	v_add_u32_e32 v0, 0x1100, v32
	v_ashrrev_i32_e32 v1, 31, v0
	v_lshl_add_u64 v[0:1], v[0:1], 2, v[34:35]
	global_store_dword v[0:1], v14, off
	v_add_u32_e32 v0, 0x1180, v32
	v_ashrrev_i32_e32 v1, 31, v0
	v_lshl_add_u64 v[0:1], v[0:1], 2, v[34:35]
	global_store_dword v[0:1], v15, off
	v_add_u32_e32 v0, 0x1800, v32
	v_ashrrev_i32_e32 v1, 31, v0
	v_lshl_add_u64 v[0:1], v[0:1], 2, v[34:35]
	global_store_dword v[0:1], v8, off
	v_add_u32_e32 v0, 0x1880, v32
	v_ashrrev_i32_e32 v1, 31, v0
	v_lshl_add_u64 v[0:1], v[0:1], 2, v[34:35]
	global_store_dword v[0:1], v9, off
	v_add_u32_e32 v0, 0x1900, v32
	v_ashrrev_i32_e32 v1, 31, v0
	v_lshl_add_u64 v[0:1], v[0:1], 2, v[34:35]
	global_store_dword v[0:1], v10, off
	v_add_u32_e32 v0, 0x1980, v32
	v_ashrrev_i32_e32 v1, 31, v0
	v_lshl_add_u64 v[0:1], v[0:1], 2, v[34:35]
	global_store_dword v[0:1], v11, off
	v_add_u32_e32 v0, 0x2000, v32
	v_ashrrev_i32_e32 v1, 31, v0
	v_lshl_add_u64 v[0:1], v[0:1], 2, v[34:35]
	global_store_dword v[0:1], v20, off
	v_add_u32_e32 v0, 0x2080, v32
	v_ashrrev_i32_e32 v1, 31, v0
	v_lshl_add_u64 v[0:1], v[0:1], 2, v[34:35]
	global_store_dword v[0:1], v21, off
	v_add_u32_e32 v0, 0x2100, v32
	v_ashrrev_i32_e32 v1, 31, v0
	v_lshl_add_u64 v[0:1], v[0:1], 2, v[34:35]
	global_store_dword v[0:1], v22, off
	v_add_u32_e32 v0, 0x2180, v32
	v_ashrrev_i32_e32 v1, 31, v0
	v_lshl_add_u64 v[0:1], v[0:1], 2, v[34:35]
	global_store_dword v[0:1], v23, off
	v_add_u32_e32 v0, 0x2800, v32
	v_ashrrev_i32_e32 v1, 31, v0
	v_lshl_add_u64 v[0:1], v[0:1], 2, v[34:35]
	global_store_dword v[0:1], v16, off
	v_add_u32_e32 v0, 0x2880, v32
	v_ashrrev_i32_e32 v1, 31, v0
	v_lshl_add_u64 v[0:1], v[0:1], 2, v[34:35]
	global_store_dword v[0:1], v17, off
	v_add_u32_e32 v0, 0x2900, v32
	v_ashrrev_i32_e32 v1, 31, v0
	v_lshl_add_u64 v[0:1], v[0:1], 2, v[34:35]
	global_store_dword v[0:1], v18, off
	v_add_u32_e32 v0, 0x2980, v32
	v_ashrrev_i32_e32 v1, 31, v0
	v_lshl_add_u64 v[0:1], v[0:1], 2, v[34:35]
	global_store_dword v[0:1], v19, off
	v_add_u32_e32 v0, 0x3000, v32
	v_ashrrev_i32_e32 v1, 31, v0
	v_lshl_add_u64 v[0:1], v[0:1], 2, v[34:35]
	global_store_dword v[0:1], v28, off
	v_add_u32_e32 v0, 0x3080, v32
	v_ashrrev_i32_e32 v1, 31, v0
	v_lshl_add_u64 v[0:1], v[0:1], 2, v[34:35]
	global_store_dword v[0:1], v29, off
	v_add_u32_e32 v0, 0x3100, v32
	v_ashrrev_i32_e32 v1, 31, v0
	v_lshl_add_u64 v[0:1], v[0:1], 2, v[34:35]
	global_store_dword v[0:1], v30, off
	v_add_u32_e32 v0, 0x3180, v32
	v_ashrrev_i32_e32 v1, 31, v0
	v_lshl_add_u64 v[0:1], v[0:1], 2, v[34:35]
	global_store_dword v[0:1], v31, off
	v_add_u32_e32 v0, 0x3800, v32
	v_ashrrev_i32_e32 v1, 31, v0
	v_lshl_add_u64 v[0:1], v[0:1], 2, v[34:35]
	global_store_dword v[0:1], v24, off
	v_add_u32_e32 v0, 0x3880, v32
	v_ashrrev_i32_e32 v1, 31, v0
	v_lshl_add_u64 v[0:1], v[0:1], 2, v[34:35]
	global_store_dword v[0:1], v25, off
	v_add_u32_e32 v0, 0x3900, v32
	v_ashrrev_i32_e32 v1, 31, v0
	v_lshl_add_u64 v[0:1], v[0:1], 2, v[34:35]
	global_store_dword v[0:1], v26, off
	v_add_u32_e32 v0, 0x3980, v32
	v_ashrrev_i32_e32 v1, 31, v0
	v_lshl_add_u64 v[0:1], v[0:1], 2, v[34:35]
	global_store_dword v[0:1], v27, off
	s_branch .LBB0_1007
